# stack: attention single barrier per tile step with V tile lagged by one, K tile 16-slot swizzle, on top of previous
# speedup vs baseline: 1.0049x; 1.0049x over previous
; #define VMW() asm volatile("s_waitcnt vmcnt(0)" ::: "memory")
; #define SLOAD_H(Kp, Vp, k0) do { S.st_v0 = load8(ROW(Vp, k0, sr)); S.st_v1 = load8(ROW(Vp, k0, 32 + sr)); S.st_k0 = load8(ROW(Kp, k0, sr)); S.st_k1 = load8(ROW(Kp, k0, 32 + sr)); } while (0)
; #define SWRITE_HK(bf) do { *(bf16x8*)(K_lds + (bf) * SHM_K + kws) = S.st_k0; *(bf16x8*)(K_lds + (bf) * SHM_K + kws + 32 * 256) = S.st_k1; } while (0)
; __device__ __forceinline__ void attn_prime(const BlockRef& cur, char* lds, Seam& S) {
;     int tid_ = threadIdx.x; asm volatile("" : "+v"(tid_));
;     const int tid = tid_, wid = __builtin_amdgcn_readfirstlane(tid >> 6), lane = tid & 63, r32 = lane & 31, hi = lane >> 5;
;     const int sr = tid >> 4, sc = (tid & 15) * 8, kws = KSWZ(sr, sc * 2); char* K_lds = lds + 2 * SHM_V;
;     for (int d0 = 0; d0 < 8; ++d0) S.qr[d0] = load8(cur.Q + (size_t)(wid * QBLK + r32) * D + d0 * 16 + hi * 8);
;     SLOAD_H(cur.K, cur.V, 0); VMW(); SWRITE_HK(0);
;     __syncthreads();
; }
; __global__ void __launch_bounds__(NTHR, 2) mega_fwd(Args args) {
;     ...
;         if (vcu < NSI) {
;             int si = vcu, sub = 0;
;     ...
;             att::BlockRef cur, nxt; MKREF(cur, si, sub);
;             att::attn_prime(cur, (char*)lds, S);
.LBB0_314:
	s_or_b64 exec, exec, s[14:15]
	s_nop 0
	s_nop 0
	s_nop 0
	s_nop 0
	s_nop 0
	s_nop 0
	s_nop 0
	s_nop 0
	s_nop 0
	s_waitcnt lgkmcnt(0)
	s_barrier
	s_movk_i32 s13, 0x100
	s_cmpk_lt_i32 s66, 0x100
	s_mov_b64 s[22:23], s[0:1]
	v_readfirstlane_b32 s24, v192
	s_mov_b64 s[20:21], s[0:1]
	s_mov_b64 s[18:19], s[0:1]
	s_mov_b64 s[14:15], s[0:1]
	s_mov_b64 s[16:17], s[0:1]
	s_cbranch_scc0 .LBB0_488
	s_load_dwordx2 s[22:23], s[22:23], 0xc8
	v_mov_b32_e32 v1, v216
	s_load_dwordx2 s[20:21], s[20:21], 0xc8
	v_mov_b32_e32 v195, 0
	s_load_dwordx2 s[18:19], s[18:19], 0xc8
	s_waitcnt lgkmcnt(0)
	s_add_u32 s25, s22, 0x2f800000
	s_addc_u32 s26, s23, 0
	s_load_dwordx2 s[14:15], s[14:15], 0xc8
	s_add_u32 s27, s20, 0x33800000
	s_addc_u32 s28, s21, 0
	s_add_u32 s30, s18, 0x37800000
	s_addc_u32 s31, s19, 0
	s_waitcnt lgkmcnt(0)
	s_add_u32 s14, s14, 0xf800000
	s_addc_u32 s15, s15, 0
	s_bfe_u32 s20, s66, 0x20004
	s_ashr_i32 s21, s66, 6
	s_lshl_b32 s18, s20, 15
	s_lshl_b32 s19, s21, 17
	s_or_b32 s18, s18, s19
	s_lshl_b32 s19, s66, 8
	s_and_b32 s19, s19, 0xf00
	s_lshl_b32 s20, s20, 14
	s_lshl_b32 s21, s21, 16
	s_xor_b32 s29, s19, 0x1f00
	s_or_b32 s20, s20, s21
	s_or_b32 s18, s18, s29
	s_or_b32 s22, s20, s29
	s_ashr_i32 s19, s18, 31
	s_ashr_i32 s23, s22, 31
	s_lshl_b64 s[18:19], s[18:19], 8
	s_ashr_i32 s21, s20, 31
	s_lshl_b64 s[22:23], s[22:23], 8
	s_add_u32 s36, s25, s22
	s_addc_u32 s37, s26, s23
	s_lshl_b64 s[20:21], s[20:21], 8
	s_add_u32 s70, s27, s20
	s_addc_u32 s71, s28, s21
	s_add_u32 s72, s30, s20
	s_addc_u32 s73, s31, s21
	s_load_dwordx2 s[16:17], s[16:17], 0xc8
	s_add_u32 s22, s14, s18
	s_addc_u32 s23, s15, s19
	v_readfirstlane_b32 s18, v1
	s_ashr_i32 s18, s18, 1
	s_movk_i32 s19, 0xffe0
	v_mov_b32_e32 v2, s18
	v_bfi_b32 v2, s19, v2, v1
	v_ashrrev_i32_e32 v3, 31, v2
	v_lshlrev_b64 v[2:3], 8, v[2:3]
	s_waitcnt vmcnt(32)
	v_lshrrev_b32_e32 v4, 1, v1
	v_lshl_add_u64 v[2:3], s[36:37], 0, v[2:3]
	v_and_b32_e32 v194, 16, v4
	v_lshl_add_u64 v[2:3], v[2:3], 0, v[194:195]
	global_load_dwordx4 v[156:159], v[2:3], off
	global_load_dwordx4 v[152:155], v[2:3], off offset:32
	global_load_dwordx4 v[148:151], v[2:3], off offset:64
	global_load_dwordx4 v[144:147], v[2:3], off offset:96
	global_load_dwordx4 v[140:143], v[2:3], off offset:128
	global_load_dwordx4 v[136:139], v[2:3], off offset:160
	global_load_dwordx4 v[132:135], v[2:3], off offset:192
	global_load_dwordx4 v[128:131], v[2:3], off offset:224
	v_ashrrev_i32_e32 v2, 4, v1
	v_lshlrev_b32_e32 v3, 4, v1
	s_movk_i32 s18, 0xf0
	v_and_b32_e32 v1, 0x70, v1
	v_and_b32_e32 v194, 0xf0, v3
	v_bitop3_b32 v1, v3, v1, s18 bitop3:0x6c
	v_ashrrev_i32_e32 v3, 31, v2
	s_waitcnt vmcnt(37)
	v_lshlrev_b32_e32 v10, 8, v2
	v_lshlrev_b64 v[2:3], 8, v[2:3]
	v_lshl_add_u64 v[4:5], s[72:73], 0, v[2:3]
	s_mov_b64 s[18:19], 0x2000
	v_lshl_add_u64 v[4:5], v[4:5], 0, v[194:195]
	v_lshl_add_u64 v[6:7], v[2:3], 0, s[18:19]
	global_load_dwordx4 v[96:99], v[4:5], off
	v_lshl_add_u64 v[4:5], s[72:73], 0, v[6:7]
	v_lshl_add_u64 v[2:3], s[70:71], 0, v[2:3]
	v_lshl_add_u64 v[4:5], v[4:5], 0, v[194:195]
	v_lshl_add_u64 v[2:3], v[2:3], 0, v[194:195]
	v_lshl_add_u64 v[6:7], s[70:71], 0, v[6:7]
	global_load_dwordx4 v[100:103], v[4:5], off
	v_lshl_add_u64 v[6:7], v[6:7], 0, v[194:195]
	global_load_dwordx4 v[2:5], v[2:3], off
	v_writelane_b32 v254, s25, 53
	global_load_dwordx4 v[6:9], v[6:7], off
	v_add3_u32 v1, 0, v10, v1
	v_and_b32_e32 v255, 0x800, v10
	v_lshrrev_b32_e32 v255, 4, v255
	v_xor_b32_e32 v1, v1, v255
	v_writelane_b32 v254, s26, 54
	s_waitcnt vmcnt(0)
	v_writelane_b32 v254, s27, 55
	s_ashr_i32 s18, s24, 3
	v_writelane_b32 v254, s28, 56
	s_and_b32 s18, s18, -8
	v_and_b32_e32 v0, 63, v192
	v_writelane_b32 v254, s30, 57
	s_cmpk_lt_i32 s18, 0x200
	v_writelane_b32 v254, s31, 58
	s_mov_b32 s48, 0
	v_bfe_u32 v193, v192, 4, 2
	s_cselect_b64 s[24:25], -1, 0
	s_mov_b32 s67, 0x41000000
	s_mov_b32 s26, 0x3e0293ee
	v_mbcnt_hi_u32_b32 v205, -1, v217
	v_lshlrev_b32_e32 v214, 2, v0
	s_mov_b32 s28, 0x3f4ccccd
	s_mov_b32 s64, 0x200000
	s_mov_b32 s65, 0x400000
	s_mov_b32 s27, 0x600000
	v_mov_b32_e32 v218, 0x358637bd
	s_mov_b32 s47, 0xf800000
	v_mov_b32_e32 v219, 0x260
	v_mov_b32_e32 v220, 0xff800000
	v_mov_b32_e32 v221, 0xf149f2ca
	s_mov_b32 s77, 0
	v_writelane_b32 v254, s18, 59
	s_waitcnt vmcnt(1)
	ds_write_b128 v1, v[2:5] offset:32768
	s_waitcnt vmcnt(0)
	ds_write_b128 v1, v[6:9] offset:40960
	v_lshlrev_b32_e32 v1, 3, v192
	v_and_b32_e32 v2, 0x78, v1
	v_lshlrev_b32_e32 v194, 1, v2
	s_waitcnt lgkmcnt(0)
	v_lshl_add_u64 v[4:5], s[16:17], 0, v[194:195]
	s_mov_b64 s[16:17], 0x17800000
	v_lshl_add_u64 v[196:197], s[14:15], 0, v[194:195]
	v_lshl_add_u64 v[198:199], v[4:5], 0, s[16:17]
	v_lshlrev_b32_e32 v215, 2, v2
	s_barrier
	s_branch .LBB0_317

; #define SBAR() __builtin_amdgcn_sched_barrier(0)
; __device__ __forceinline__ int v_st(int k, int c) { const int kk = (k & ~0xC) | ((k & 4) << 1) | ((k & 8) >> 1); return ((kk >> 3) * 4 + (c >> 5)) * 512 + ((kk & 7) * 32 + (c & 31)) * 2; }
; __device__ __forceinline__ int v_rd_base(int lane) { return ((lane & 3) << 3) | (((lane >> 2) & 3) << 6) | (((lane >> 4) & 1) << 5) | (((lane >> 5) & 1) << 8); }
; #define VMW() asm volatile("s_waitcnt vmcnt(0)" ::: "memory")
; #define SWRITE_HV(bf) do { *(bf16x8*)(V_lds + (bf) * SHM_V + vst0) = S.st_v0; *(bf16x8*)(V_lds + (bf) * SHM_V + vst1) = S.st_v1; } while (0)
; template <int KB>
; __device__ __forceinline__ void qkt(f32x16& p0, f32x16& p1, const char* K_lds, int r32, int hi, const bf16x8* qr) {
;     p0 = f32x16{}; p1 = f32x16{};
;     const char* kb[4];
; #pragma unroll
;     for (int dd = 0; dd < 4; ++dd) kb[dd] = K_lds + KB * SHM_K + KSWZ(r32, (dd * 16 + hi * 8) * 2);
; #pragma unroll
;     for (int d0 = 0; d0 < 8; ++d0) { const char* a = kb[d0 & 3] + (d0 >> 2) * 128;
;         bf16x8 b0 = *reinterpret_cast<const bf16x8*>(a);
;         bf16x8 b1 = *reinterpret_cast<const bf16x8*>(a + 32 * 256);
;         p0 = __builtin_amdgcn_mfma_f32_32x32x16_bf16(b0, qr[d0], p0, 0, 0, 0);
;         p1 = __builtin_amdgcn_mfma_f32_32x32x16_bf16(b1, qr[d0], p1, 0, 0, 0); }
; }
; __device__ __forceinline__ void attn_block(const BlockRef& cur, const BlockRef& nxt, char* lds, Seam& S) {
;     ...
;     const int NT = (cur.P0 + QB) / KVBLK;
;     const int qlo = cur.P0 + wid * QBLK;
;     char* V_lds = lds; char* K_lds = lds + 2 * SHM_V;
;     float* ws = (float*)(lds + 2 * SHM_V + 2 * SHM_K) + wid * 64; float* li_l = ws, * al_l = ws + 32;
;     float m_reg = -1e30f, l_reg = 0; f32x16 o[4] = {};
;     const int sr = tid >> 4, sc = (tid & 15) * 8, vst0 = v_st(sr, sc), vst1 = v_st(32 + sr, sc), kws = KSWZ(sr, sc * 2);
;     const int vb0 = (int)(uintptr_t)V_lds + v_rd_base(lane);
;     const bf16* Kh = cur.K; const bf16* Vh = cur.V;
;     ...
;     constexpr int NQL = 8;
;     ...
;     f32x16 pA0, pA1, pB0, pB1; float mnA, mnB, alA, alB; bf16x8 pa0, pa1, pa2, pa3;
;     SWRITE_HV(0); SBAR();
;     if (NT > 1) { SLOAD_H(Kh, Vh, KBASE(1)); }
;     SBAR(); qkt<0>(pA0, pA1, K_lds, r32, hi, S.qr);
;     MASKT(pA0, pA1, 0); partialSM(pA0, pA1, m_reg, mnA, alA);
;     if (NT > 1) { VMW(); SWRITE_H(1); }
;     __syncthreads();
.LBB0_319:
	v_mov_b32_e32 v222, v216
	s_add_i32 s78, s29, 0x100
	v_ashrrev_i32_e32 v202, 4, v222
	v_add_u32_e32 v206, 32, v202
	s_waitcnt lgkmcnt(1)
	v_and_b32_e32 v1, 0xfffff0, v202
	v_lshlrev_b32_e32 v2, 1, v202
	v_and_b32_e32 v4, 0xfffff0, v206
	v_lshlrev_b32_e32 v5, 1, v206
	v_lshlrev_b32_e32 v0, 3, v222
	v_and_or_b32 v1, v2, 8, v1
	v_and_or_b32 v4, v5, 8, v4
	v_readfirstlane_b32 s39, v222
	v_and_b32_e32 v204, 0x78, v0
	v_lshrrev_b32_e32 v2, 1, v202
	v_lshrrev_b32_e32 v1, 1, v1
	v_bfe_u32 v0, v0, 5, 2
	s_waitcnt lgkmcnt(0)
	v_and_b32_e32 v3, 3, v202
	v_lshrrev_b32_e32 v4, 1, v4
	s_ashr_i32 s38, s39, 1
	s_and_b32 s39, s39, 0x3fffffc0
	v_or_b32_e32 v1, v1, v0
	v_and_or_b32 v2, v2, 4, v3
	v_lshlrev_b32_e32 v194, 1, v204
	v_or_b32_e32 v0, v4, v0
	s_lshl_b32 s39, s39, 2
	v_lshlrev_b32_e32 v1, 9, v1
	v_lshlrev_b32_e32 v2, 6, v2
	v_and_b32_e32 v3, 48, v194
	v_lshlrev_b32_e32 v0, 9, v0
	v_and_b32_e32 v84, 63, v222
	s_and_b32 s68, s38, 0xffffffe0
	s_add_i32 s69, s39, 0
	v_or3_b32 v1, v1, v2, v3
	v_or3_b32 v0, v0, v2, v3
	v_lshlrev_b32_e32 v2, 8, v202
	v_and_b32_e32 v3, 0x70, v222
	v_lshlrev_b32_e32 v8, 4, v222
	s_lshr_b32 s79, s78, 6
	s_add_i32 s38, s68, s29
	s_add_i32 s69, s69, 0x10000
	v_bitop3_b32 v85, v194, v2, v3 bitop3:0xde
	v_lshlrev_b32_e32 v2, 3, v84
	v_and_b32_e32 v3, 0xc0, v8
	v_lshlrev_b32_e32 v4, 1, v222
	v_and_or_b32 v3, v2, 24, v3
	v_and_b32_e32 v4, 32, v4
	v_and_b32_e32 v2, 0x100, v2
	s_cmp_lg_u32 0, -1
	v_or3_b32 v2, v3, v4, v2
	s_cselect_b32 s39, 0, 0
	v_and_b32_e32 v223, 31, v222
	v_bfe_u32 v224, v222, 5, 1
	s_mov_b32 s80, 2
	v_add_u32_e32 v225, s39, v2
	v_add_u32_e32 v231, 0, v1
	v_add_u32_e32 v232, 0, v0
	ds_write_b128 v231, v[96:99]
	ds_write_b128 v232, v[100:103]
	v_ashrrev_i32_e32 v203, 31, v202
	v_lshlrev_b64 v[0:1], 8, v[202:203]
	s_mov_b64 s[40:41], 0x4000
	v_lshl_add_u64 v[2:3], v[0:1], 0, s[40:41]
	s_mov_b64 s[40:41], 0x6000
	v_lshl_add_u64 v[4:5], s[72:73], 0, v[2:3]
	v_lshl_add_u64 v[0:1], v[0:1], 0, s[40:41]
	v_lshl_add_u64 v[2:3], s[70:71], 0, v[2:3]
	v_lshl_add_u64 v[4:5], v[4:5], 0, v[194:195]
	v_lshl_add_u64 v[6:7], s[72:73], 0, v[0:1]
	v_lshl_add_u64 v[2:3], v[2:3], 0, v[194:195]
	v_lshl_add_u64 v[0:1], s[70:71], 0, v[0:1]
	v_lshl_add_u64 v[6:7], v[6:7], 0, v[194:195]
	global_load_dwordx4 v[48:51], v[4:5], off
	global_load_dwordx4 v[52:55], v[6:7], off
	v_lshl_add_u64 v[0:1], v[0:1], 0, v[194:195]
	global_load_dwordx4 v[56:59], v[2:3], off
	global_load_dwordx4 v[60:63], v[0:1], off
	v_lshlrev_b32_e32 v200, 4, v224
	v_and_b32_e32 v73, 0x70, v8
	v_lshlrev_b32_e32 v72, 8, v223
	v_and_b32_e32 v255, 8, v223
	v_lshl_or_b32 v72, v255, 4, v72
	v_xad_u32 v0, v200, v73, 0
	v_add_u32_e32 v201, v0, v72
	v_xor_b32_e32 v250, 0x80, v201
	ds_read_b128 v[0:3], v201 offset:32768
	ds_read_b128 v[4:7], v250 offset:32768
	v_or_b32_e32 v8, 32, v200
	s_waitcnt vmcnt(11) lgkmcnt(1)
	v_mfma_f32_32x32x16_bf16 v[32:47], v[0:3], v[156:159], 0
	ds_read_b128 v[0:3], v201 offset:40960
	v_xad_u32 v8, v8, v73, 0
	v_add_u32_e32 v230, v8, v72
	v_xor_b32_e32 v251, 0x80, v230
	ds_read_b128 v[8:11], v250 offset:40960
	v_or_b32_e32 v64, 64, v200
	v_xad_u32 v64, v64, v73, 0
	v_add_u32_e32 v229, v64, v72
	v_xor_b32_e32 v252, 0x80, v229
	s_waitcnt lgkmcnt(1)
	v_mfma_f32_32x32x16_bf16 v[16:31], v[0:3], v[156:159], 0
	ds_read_b128 v[0:3], v230 offset:32768
	ds_read_b128 v[12:15], v251 offset:32768
	ds_read_b128 v[64:67], v251 offset:40960
	v_or_b32_e32 v74, 0x60, v200
	v_xad_u32 v73, v74, v73, 0
	v_add_u32_e32 v207, v73, v72
	v_xor_b32_e32 v253, 0x80, v207
	s_mov_b32 s49, s48
	s_mov_b32 s50, s48
	s_waitcnt vmcnt(10) lgkmcnt(2)
	v_mfma_f32_32x32x16_bf16 v[32:47], v[0:3], v[152:155], v[32:47]
	ds_read_b128 v[0:3], v230 offset:40960
	s_mov_b32 s51, s48
	s_mov_b32 s52, s48
	s_mov_b32 s53, s48
	s_mov_b32 s54, s48
	s_mov_b32 s55, s48
	s_mov_b32 s56, s48
	s_waitcnt lgkmcnt(0)
	v_mfma_f32_32x32x16_bf16 v[16:31], v[0:3], v[152:155], v[16:31]
	ds_read_b128 v[0:3], v229 offset:32768
	ds_read_b128 v[68:71], v252 offset:32768
	ds_read_b128 v[72:75], v252 offset:40960
	s_mov_b32 s57, s48
	s_mov_b32 s58, s48
	s_mov_b32 s59, s48
	s_mov_b32 s60, s48
	s_mov_b32 s61, s48
	s_waitcnt vmcnt(9) lgkmcnt(2)
	v_mfma_f32_32x32x16_bf16 v[32:47], v[0:3], v[148:151], v[32:47]
	ds_read_b128 v[0:3], v229 offset:40960
	s_mov_b32 s62, s48
	s_mov_b32 s63, s48
	v_add_u32_e32 v226, 0, v85
	v_and_b32_e32 v255, 8, v202
	v_lshlrev_b32_e32 v255, 4, v255
	v_xor_b32_e32 v226, v226, v255
	v_lshl_add_u64 v[208:209], s[72:73], 0, v[194:195]
	s_mov_b32 s40, 0xffffc000
	s_mov_b32 s41, -1
	v_lshl_add_u64 v[208:209], v[208:209], 0, s[40:41]
	v_lshl_add_u64 v[210:211], s[70:71], 0, v[194:195]
	v_lshl_add_u32 v227, v223, 2, s69
	s_waitcnt lgkmcnt(0)
	v_mfma_f32_32x32x16_bf16 v[16:31], v[0:3], v[148:151], v[16:31]
	ds_read_b128 v[0:3], v207 offset:32768
	ds_read_b128 v[76:79], v253 offset:32768
	v_mov_b32_e32 v228, 0
	s_waitcnt vmcnt(8) lgkmcnt(1)
	v_mfma_f32_32x32x16_bf16 v[32:47], v[0:3], v[144:147], v[32:47]
	ds_read_b128 v[0:3], v207 offset:40960
	ds_read_b128 v[80:83], v253 offset:40960
	s_waitcnt vmcnt(0)
	s_waitcnt vmcnt(3)
	ds_write_b128 v231, v[48:51] offset:16384
	s_waitcnt vmcnt(2)
	ds_write_b128 v232, v[52:55] offset:16384
	s_waitcnt vmcnt(1)
	ds_write_b128 v226, v[56:59] offset:49152
	s_waitcnt vmcnt(0)
	ds_write_b128 v226, v[60:63] offset:57344
	s_waitcnt lgkmcnt(0)
	s_barrier
; #define SBAR() __builtin_amdgcn_sched_barrier(0)
; __device__ __forceinline__ int v_st(int k, int c) { const int kk = (k & ~0xC) | ((k & 4) << 1) | ((k & 8) >> 1); return ((kk >> 3) * 4 + (c >> 5)) * 512 + ((kk & 7) * 32 + (c & 31)) * 2; }
; __device__ __forceinline__ int v_rd_base(int lane) { return ((lane & 3) << 3) | (((lane >> 2) & 3) << 6) | (((lane >> 4) & 1) << 5) | (((lane >> 5) & 1) << 8); }
; #define SLOAD_H(Kp, Vp, k0) do { S.st_v0 = load8(ROW(Vp, k0, sr)); S.st_v1 = load8(ROW(Vp, k0, 32 + sr)); S.st_k0 = load8(ROW(Kp, k0, sr)); S.st_k1 = load8(ROW(Kp, k0, 32 + sr)); } while (0)
; #define SWRITE_HV(bf) do { *(bf16x8*)(V_lds + (bf) * SHM_V + vst0) = S.st_v0; *(bf16x8*)(V_lds + (bf) * SHM_V + vst1) = S.st_v1; } while (0)
; __device__ __forceinline__ void partialSM(f32x16& p0, f32x16& p1, float& m_reg, float& mn, float& alpha) {
;     float pmax = p0[0]; for (int r = 1; r < 16; ++r) pmax = fmaxf(pmax, p0[r]); for (int r = 0; r < 16; ++r) pmax = fmaxf(pmax, p1[r]);
;     { auto rr = __builtin_amdgcn_permlane32_swap(__float_as_uint(pmax), __float_as_uint(pmax), false, false);
;       pmax = fmaxf(__uint_as_float(rr[0]), __uint_as_float(rr[1])); }
;     constexpr float C2 = 1.4426950408889634f * SCALE;
;     if (__builtin_expect(__all((pmax - m_reg) * SCALE <= THR), 1)) { mn = m_reg; alpha = 1.f; }
;     else { mn = fmaxf(m_reg, pmax); alpha = __builtin_amdgcn_exp2f((m_reg - mn) * C2); m_reg = mn; }
;     const float mnL = -mn * C2;
;     for (int r = 0; r < 16; ++r) p0[r] = fmaf(p0[r], C2, mnL); for (int r = 0; r < 16; ++r) p1[r] = fmaf(p1[r], C2, mnL);
;     for (int r = 0; r < 16; ++r) p0[r] = __builtin_amdgcn_exp2f(p0[r]);
; }
; __device__ __forceinline__ void attn_block(const BlockRef& cur, const BlockRef& nxt, char* lds, Seam& S) {
;     ...
;     float m_reg = -1e30f, l_reg = 0; f32x16 o[4] = {};
;     const int sr = tid >> 4, sc = (tid & 15) * 8, vst0 = v_st(sr, sc), vst1 = v_st(32 + sr, sc), kws = KSWZ(sr, sc * 2);
;     const int vb0 = (int)(uintptr_t)V_lds + v_rd_base(lane);
;     const bf16* Kh = cur.K; const bf16* Vh = cur.V;
;     ...
;     constexpr int NQL = 8;
;     ...
;     f32x16 pA0, pA1, pB0, pB1; float mnA, mnB, alA, alB; bf16x8 pa0, pa1, pa2, pa3;
;     SWRITE_HV(0); SBAR();
;     if (NT > 1) { SLOAD_H(Kh, Vh, KBASE(1)); }
;     SBAR(); qkt<0>(pA0, pA1, K_lds, r32, hi, S.qr);
;     MASKT(pA0, pA1, 0); partialSM(pA0, pA1, m_reg, mnA, alA);
	v_mfma_f32_32x32x16_bf16 v[32:47], v[4:7], v[140:143], v[32:47]
	v_mfma_f32_32x32x16_bf16 v[16:31], v[0:3], v[144:147], v[16:31]
	v_mfma_f32_32x32x16_bf16 v[32:47], v[12:15], v[136:139], v[32:47]
	v_mfma_f32_32x32x16_bf16 v[16:31], v[8:11], v[140:143], v[16:31]
	v_mov_b64_e32 v[0:1], s[48:49]
	v_mov_b64_e32 v[2:3], s[50:51]
	v_mov_b64_e32 v[4:5], s[52:53]
	v_mov_b64_e32 v[6:7], s[54:55]
	v_mov_b64_e32 v[8:9], s[56:57]
	v_mov_b64_e32 v[10:11], s[58:59]
	v_mov_b64_e32 v[12:13], s[60:61]
	v_mfma_f32_32x32x16_bf16 v[32:47], v[68:71], v[132:135], v[32:47]
	v_mov_b64_e32 v[14:15], s[62:63]
	s_or_b32 s49, s38, 63
	s_cmp_lt_i32 s38, 0
	s_cselect_b64 vcc, -1, 0
	v_mov_b64_e32 v[62:63], v[14:15]
	v_readlane_b32 s60, v254, 51
	v_cmp_gt_u32_e64 s[38:39], 32, v84
	v_mfma_f32_32x32x16_bf16 v[16:31], v[64:67], v[136:139], v[16:31]
	s_movk_i32 s50, 0x80
	v_mov_b64_e32 v[60:61], v[12:13]
	v_mov_b64_e32 v[58:59], v[10:11]
	v_mov_b64_e32 v[56:57], v[8:9]
	v_mov_b64_e32 v[54:55], v[6:7]
	v_mov_b64_e32 v[52:53], v[4:5]
	v_mov_b64_e32 v[50:51], v[2:3]
	v_mfma_f32_32x32x16_bf16 v[32:47], v[76:79], v[128:131], v[32:47]
	v_mov_b64_e32 v[48:49], v[0:1]
	v_readlane_b32 s61, v254, 52
	v_mfma_f32_32x32x16_bf16 v[16:31], v[72:75], v[132:135], v[16:31]
	s_nop 8
	v_cndmask_b32_e32 v64, v32, v220, vcc
	v_cndmask_b32_e32 v33, v33, v220, vcc
	v_max_f32_e32 v32, v33, v33
	v_max_f32_e32 v65, v64, v64
	v_cndmask_b32_e32 v35, v35, v220, vcc
	v_cndmask_b32_e32 v34, v34, v220, vcc
	v_max_f32_e32 v32, v65, v32
	v_mfma_f32_32x32x16_bf16 v[16:31], v[80:83], v[128:131], v[16:31]
	v_cndmask_b32_e32 v37, v37, v220, vcc
	v_cndmask_b32_e32 v36, v36, v220, vcc
	v_max3_f32 v32, v32, v34, v35
	v_cndmask_b32_e32 v39, v39, v220, vcc
	v_cndmask_b32_e32 v38, v38, v220, vcc
	v_max3_f32 v32, v32, v36, v37
	v_cndmask_b32_e32 v41, v41, v220, vcc
	v_cndmask_b32_e32 v40, v40, v220, vcc
	v_max3_f32 v32, v32, v38, v39
	v_cndmask_b32_e32 v43, v43, v220, vcc
	v_cndmask_b32_e32 v42, v42, v220, vcc
	v_max3_f32 v32, v32, v40, v41
	v_cndmask_b32_e32 v45, v45, v220, vcc
	v_cndmask_b32_e32 v44, v44, v220, vcc
	v_max3_f32 v32, v32, v42, v43
	v_cndmask_b32_e32 v47, v47, v220, vcc
	v_cndmask_b32_e32 v46, v46, v220, vcc
	v_max3_f32 v32, v32, v44, v45
	v_cndmask_b32_e32 v17, v17, v220, vcc
	v_cndmask_b32_e32 v16, v16, v220, vcc
	v_max3_f32 v32, v32, v46, v47
	v_cndmask_b32_e32 v19, v19, v220, vcc
	v_cndmask_b32_e32 v18, v18, v220, vcc
	v_max3_f32 v32, v32, v16, v17
	v_cndmask_b32_e32 v21, v21, v220, vcc
	v_cndmask_b32_e32 v20, v20, v220, vcc
	v_max3_f32 v32, v32, v18, v19
	v_cndmask_b32_e32 v23, v23, v220, vcc
	v_cndmask_b32_e32 v22, v22, v220, vcc
	v_max3_f32 v32, v32, v20, v21
	v_cndmask_b32_e32 v25, v25, v220, vcc
	v_cndmask_b32_e32 v24, v24, v220, vcc
	v_max3_f32 v32, v32, v22, v23
	v_cndmask_b32_e32 v27, v27, v220, vcc
	v_cndmask_b32_e32 v26, v26, v220, vcc
	v_max3_f32 v32, v32, v24, v25
	v_cndmask_b32_e32 v29, v29, v220, vcc
	v_cndmask_b32_e32 v28, v28, v220, vcc
	v_max3_f32 v32, v32, v26, v27
	v_cndmask_b32_e32 v31, v31, v220, vcc
	v_cndmask_b32_e32 v30, v30, v220, vcc
	v_max3_f32 v32, v32, v28, v29
	v_max3_f32 v32, v32, v30, v31
	v_mov_b32_e32 v65, v32
	s_nop 1
	v_permlane32_swap_b32_e32 v32, v65
	v_max_f32_e32 v65, v65, v65
	v_max_f32_e32 v32, v32, v32
	v_max_f32_e32 v32, v32, v65
	v_add_f32_e32 v65, 0x7149f2ca, v32
	v_mul_f32_e32 v65, 0x3db504f3, v65
	v_max_f32_e32 v32, 0xf149f2ca, v32
	v_cmp_ge_f32_e32 vcc, s67, v65
	v_sub_f32_e32 v65, 0xf149f2ca, v32
	v_mul_f32_e32 v65, 0x3e0293ee, v65
	v_exp_f32_e32 v65, v65
	s_cmp_eq_u64 vcc, exec
	s_cselect_b64 vcc, -1, 0
	v_cndmask_b32_e32 v176, v32, v221, vcc
	v_mul_f32_e32 v32, 0xbe0293ee, v176
	v_cndmask_b32_e64 v233, v65, 1.0, vcc
	v_mov_b32_e32 v65, v32
	v_fmamk_f32 v64, v64, 0x3e0293ee, v32
	v_fmamk_f32 v33, v33, 0x3e0293ee, v32
	v_fmamk_f32 v34, v34, 0x3e0293ee, v32
	v_fmamk_f32 v35, v35, 0x3e0293ee, v32
	v_fmamk_f32 v36, v36, 0x3e0293ee, v32
	v_fmamk_f32 v37, v37, 0x3e0293ee, v32
	v_fmamk_f32 v38, v38, 0x3e0293ee, v32
	v_fmamk_f32 v39, v39, 0x3e0293ee, v32
	v_fmamk_f32 v40, v40, 0x3e0293ee, v32
	v_fmamk_f32 v41, v41, 0x3e0293ee, v32
	v_fmamk_f32 v42, v42, 0x3e0293ee, v32
	v_fmamk_f32 v43, v43, 0x3e0293ee, v32
	v_fmamk_f32 v44, v44, 0x3e0293ee, v32
	v_fmamk_f32 v45, v45, 0x3e0293ee, v32
	v_fmamk_f32 v46, v46, 0x3e0293ee, v32
	v_fmac_f32_e32 v65, 0x3e0293ee, v47
	v_exp_f32_e32 v169, v64
	v_exp_f32_e32 v170, v33
	v_exp_f32_e32 v171, v34
	v_exp_f32_e32 v173, v35
	v_exp_f32_e32 v174, v36
	v_exp_f32_e32 v177, v37
	v_exp_f32_e32 v172, v38
	v_exp_f32_e32 v175, v39
	v_exp_f32_e32 v161, v40
	v_exp_f32_e32 v163, v41
	v_exp_f32_e32 v164, v42
	v_exp_f32_e32 v167, v43
	v_exp_f32_e32 v162, v44
	v_exp_f32_e32 v165, v45
	v_exp_f32_e32 v166, v46
	v_exp_f32_e32 v168, v65
	v_pk_fma_f32 v[114:115], v[30:31], s[26:27], v[32:33] op_sel_hi:[1,0,0]
	v_pk_fma_f32 v[120:121], v[28:29], s[26:27], v[32:33] op_sel_hi:[1,0,0]
	v_pk_fma_f32 v[124:125], v[26:27], s[26:27], v[32:33] op_sel_hi:[1,0,0]
	v_pk_fma_f32 v[112:113], v[24:25], s[26:27], v[32:33] op_sel_hi:[1,0,0]
	v_pk_fma_f32 v[116:117], v[22:23], s[26:27], v[32:33] op_sel_hi:[1,0,0]
	v_pk_fma_f32 v[118:119], v[20:21], s[26:27], v[32:33] op_sel_hi:[1,0,0]
	v_pk_fma_f32 v[122:123], v[18:19], s[26:27], v[32:33] op_sel_hi:[1,0,0]
	v_pk_fma_f32 v[126:127], v[16:17], s[26:27], v[32:33] op_sel_hi:[1,0,0]
	v_mov_b64_e32 v[46:47], v[14:15]
	v_mov_b64_e32 v[30:31], v[14:15]
	v_mov_b64_e32 v[44:45], v[12:13]
	v_mov_b64_e32 v[42:43], v[10:11]
	v_mov_b64_e32 v[40:41], v[8:9]
	v_mov_b64_e32 v[38:39], v[6:7]
	v_mov_b64_e32 v[36:37], v[4:5]
	v_mov_b64_e32 v[34:35], v[2:3]
	v_mov_b64_e32 v[32:33], v[0:1]
	v_mov_b64_e32 v[28:29], v[12:13]
	v_mov_b64_e32 v[26:27], v[10:11]
	v_mov_b64_e32 v[24:25], v[8:9]
	v_mov_b64_e32 v[22:23], v[6:7]
	v_mov_b64_e32 v[20:21], v[4:5]
	v_mov_b64_e32 v[18:19], v[2:3]
	v_mov_b64_e32 v[16:17], v[0:1]
; __device__ __forceinline__ void finishSM(f32x16& p0, f32x16& p1, float alpha, float& l_reg, bf16x8& pa0, bf16x8& pa1, bf16x8& pa2, bf16x8& pa3) {
;     for (int r = 0; r < 16; ++r) p1[r] = __builtin_amdgcn_exp2f(p1[r]);
;     float ps = 0; for (int r = 0; r < 16; ++r) ps += p0[r]; for (int r = 0; r < 16; ++r) ps += p1[r];
;     { auto rr = __builtin_amdgcn_permlane32_swap(__float_as_uint(ps), __float_as_uint(ps), false, false);
;       ps = __uint_as_float(rr[0]) + __uint_as_float(rr[1]); }
;     l_reg = l_reg * alpha + ps;
;     ...
;     PK4(p0, 0, pa0); PK4(p0, 8, pa1); PK4(p1, 0, pa2); PK4(p1, 8, pa3);
;     ...
; }
; template <int KB>
; __device__ __forceinline__ void qkt(f32x16& p0, f32x16& p1, const char* K_lds, int r32, int hi, const bf16x8* qr) {
;     p0 = f32x16{}; p1 = f32x16{};
;     const char* kb[4];
; #pragma unroll
;     for (int dd = 0; dd < 4; ++dd) kb[dd] = K_lds + KB * SHM_K + KSWZ(r32, (dd * 16 + hi * 8) * 2);
; #pragma unroll
;     for (int d0 = 0; d0 < 8; ++d0) { const char* a = kb[d0 & 3] + (d0 >> 2) * 128;
;         bf16x8 b0 = *reinterpret_cast<const bf16x8*>(a);
;         bf16x8 b1 = *reinterpret_cast<const bf16x8*>(a + 32 * 256);
;         p0 = __builtin_amdgcn_mfma_f32_32x32x16_bf16(b0, qr[d0], p0, 0, 0, 0);
;         p1 = __builtin_amdgcn_mfma_f32_32x32x16_bf16(b1, qr[d0], p1, 0, 0, 0); }
; }
.LBB0_320:
	v_xor_b32_e32 v250, 0x80, v201
	v_xor_b32_e32 v251, 0x80, v230
	v_xor_b32_e32 v252, 0x80, v229
	v_xor_b32_e32 v253, 0x80, v207
	ds_read_b128 v[64:67], v201 offset:49152
	ds_read_b128 v[68:71], v201 offset:57344
	ds_read_b128 v[96:99], v230 offset:49152
	ds_read_b128 v[100:103], v230 offset:57344
	v_exp_f32_e32 v104, v126
	v_exp_f32_e32 v105, v127
	s_waitcnt lgkmcnt(3)
	v_mfma_f32_32x32x16_bf16 v[80:95], v[64:67], v[156:159], 0
	v_exp_f32_e32 v106, v122
	v_exp_f32_e32 v107, v123
	v_exp_f32_e32 v108, v118
	v_exp_f32_e32 v109, v119
	v_exp_f32_e32 v110, v116
	v_exp_f32_e32 v111, v117
	v_exp_f32_e32 v112, v112
	s_waitcnt lgkmcnt(2)
	v_mfma_f32_32x32x16_bf16 v[64:79], v[68:71], v[156:159], 0
	v_exp_f32_e32 v113, v113
	v_exp_f32_e32 v116, v124
	v_exp_f32_e32 v117, v125
	v_exp_f32_e32 v118, v120
	v_exp_f32_e32 v119, v121
	v_exp_f32_e32 v114, v114
	v_exp_f32_e32 v115, v115
	s_waitcnt lgkmcnt(1)
	v_mfma_f32_32x32x16_bf16 v[80:95], v[96:99], v[152:155], v[80:95]
	s_waitcnt lgkmcnt(0)
	v_mfma_f32_32x32x16_bf16 v[64:79], v[100:103], v[152:155], v[64:79]
	ds_read_b128 v[96:99], v229 offset:49152
	ds_read_b128 v[100:103], v229 offset:57344
	s_waitcnt lgkmcnt(1)
	v_mfma_f32_32x32x16_bf16 v[80:95], v[96:99], v[148:151], v[80:95]
	s_waitcnt lgkmcnt(0)
	v_mfma_f32_32x32x16_bf16 v[64:79], v[100:103], v[148:151], v[64:79]
	ds_read_b128 v[96:99], v207 offset:49152
	ds_read_b128 v[100:103], v207 offset:57344
	s_waitcnt lgkmcnt(1)
	v_mfma_f32_32x32x16_bf16 v[80:95], v[96:99], v[144:147], v[80:95]
	s_waitcnt lgkmcnt(0)
	v_mfma_f32_32x32x16_bf16 v[64:79], v[100:103], v[144:147], v[64:79]
	ds_read_b128 v[96:99], v250 offset:49152
	ds_read_b128 v[100:103], v250 offset:57344
	s_waitcnt lgkmcnt(1)
	v_mfma_f32_32x32x16_bf16 v[80:95], v[96:99], v[140:143], v[80:95]
	s_waitcnt lgkmcnt(0)
	v_mfma_f32_32x32x16_bf16 v[64:79], v[100:103], v[140:143], v[64:79]
	ds_read_b128 v[96:99], v251 offset:49152
	ds_read_b128 v[100:103], v251 offset:57344
	s_waitcnt lgkmcnt(1)
	v_mfma_f32_32x32x16_bf16 v[80:95], v[96:99], v[136:139], v[80:95]
	s_waitcnt lgkmcnt(0)
	v_mfma_f32_32x32x16_bf16 v[64:79], v[100:103], v[136:139], v[64:79]
	ds_read_b128 v[96:99], v252 offset:49152
	ds_read_b128 v[100:103], v252 offset:57344
	s_waitcnt lgkmcnt(1)
	v_mfma_f32_32x32x16_bf16 v[80:95], v[96:99], v[132:135], v[80:95]
	s_waitcnt lgkmcnt(0)
	v_mfma_f32_32x32x16_bf16 v[64:79], v[100:103], v[132:135], v[64:79]
	ds_read_b128 v[96:99], v253 offset:49152
	ds_read_b128 v[100:103], v253 offset:57344
	ds_read_b64_tr_b16 v[238:239], v225 offset:0
	ds_read_b64_tr_b16 v[240:241], v225 offset:0x800
	ds_read_b64_tr_b16 v[242:243], v225 offset:0x1000
	ds_read_b64_tr_b16 v[244:245], v225 offset:0x1800
	ds_read_b64_tr_b16 v[246:247], v225 offset:0x2000
	ds_read_b64_tr_b16 v[248:249], v225 offset:0x2800
	ds_read_b64_tr_b16 v[250:251], v225 offset:0x3000
	ds_read_b64_tr_b16 v[252:253], v225 offset:0x3800
	s_waitcnt lgkmcnt(9)
	v_mfma_f32_32x32x16_bf16 v[80:95], v[96:99], v[128:131], v[80:95]
	v_add_f32_e32 v96, 0, v169
	v_add_f32_e32 v96, v170, v96
	v_add_f32_e32 v96, v171, v96
	v_add_f32_e32 v96, v173, v96
	v_add_f32_e32 v96, v174, v96
	v_add_f32_e32 v96, v177, v96
	v_add_f32_e32 v96, v172, v96
	v_add_f32_e32 v96, v175, v96
	v_add_f32_e32 v96, v161, v96
	v_add_f32_e32 v96, v163, v96
	v_add_f32_e32 v96, v164, v96
	v_add_f32_e32 v96, v167, v96
	v_add_f32_e32 v96, v162, v96
	v_add_f32_e32 v96, v165, v96
	v_add_f32_e32 v96, v166, v96
	v_add_f32_e32 v96, v168, v96
	v_add_f32_e32 v96, v104, v96
	v_add_f32_e32 v96, v105, v96
	v_add_f32_e32 v96, v106, v96
	v_add_f32_e32 v96, v107, v96
	v_add_f32_e32 v96, v108, v96
	v_add_f32_e32 v96, v109, v96
	v_add_f32_e32 v96, v110, v96
	v_add_f32_e32 v96, v111, v96
	v_add_f32_e32 v96, v112, v96
	v_add_f32_e32 v96, v113, v96
	s_waitcnt lgkmcnt(8)
	v_mfma_f32_32x32x16_bf16 v[64:79], v[100:103], v[128:131], v[64:79]
	v_add_f32_e32 v96, v116, v96
	v_add_f32_e32 v96, v117, v96
	v_add_f32_e32 v96, v118, v96
	v_add_f32_e32 v96, v119, v96
	v_add_f32_e32 v96, v114, v96
	v_add_f32_e32 v194, v115, v96
	v_mov_b32_e32 v234, v194
	v_cvt_pk_bf16_f32 v96, v169, v170
	v_cvt_pk_bf16_f32 v97, v171, v173
	v_cvt_pk_bf16_f32 v98, v174, v177
	v_cvt_pk_bf16_f32 v99, v172, v175
	v_permlane32_swap_b32_e32 v194, v234
	v_permlane32_swap_b32_e32 v96, v98
	v_permlane32_swap_b32_e32 v97, v99
	v_cvt_pk_bf16_f32 v100, v161, v163
	v_cvt_pk_bf16_f32 v101, v164, v167
	v_cvt_pk_bf16_f32 v102, v162, v165
	v_cvt_pk_bf16_f32 v103, v166, v168
	v_cvt_pk_bf16_f32 v104, v104, v105
	v_cvt_pk_bf16_f32 v105, v106, v107
	v_cvt_pk_bf16_f32 v106, v108, v109
	v_cvt_pk_bf16_f32 v107, v110, v111
	v_cvt_pk_bf16_f32 v108, v112, v113
	v_cvt_pk_bf16_f32 v109, v116, v117
	v_cvt_pk_bf16_f32 v110, v118, v119
	v_cvt_pk_bf16_f32 v111, v114, v115
	v_permlane32_swap_b32_e32 v100, v102
	v_permlane32_swap_b32_e32 v101, v103
	v_permlane32_swap_b32_e32 v104, v106
	v_permlane32_swap_b32_e32 v105, v107
	v_permlane32_swap_b32_e32 v108, v110
	v_permlane32_swap_b32_e32 v109, v111
	v_add_u32_e32 v212, s50, v202
	v_ashrrev_i32_e32 v213, 31, v212
	v_add_u32_e32 v116, 32, v212
	v_lshlrev_b64 v[112:113], 8, v[212:213]
	v_ashrrev_i32_e32 v117, 31, v116
	v_lshl_add_u64 v[114:115], v[208:209], 0, v[112:113]
	v_lshlrev_b64 v[116:117], 8, v[116:117]
	v_lshl_add_u64 v[112:113], v[210:211], 0, v[112:113]
	v_lshl_add_u64 v[118:119], v[208:209], 0, v[116:117]
	global_load_dwordx4 v[160:163], v[114:115], off
	global_load_dwordx4 v[164:167], v[118:119], off
	v_lshl_add_u64 v[114:115], v[210:211], 0, v[116:117]
	global_load_dwordx4 v[168:171], v[112:113], off
	global_load_dwordx4 v[172:175], v[114:115], off
	s_waitcnt lgkmcnt(0)
; #define SBAR() __builtin_amdgcn_sched_barrier(0)
; #define VMW() asm volatile("s_waitcnt vmcnt(0)" ::: "memory")
; #define SLOAD_H(Kp, Vp, k0) do { S.st_v0 = load8(ROW(Vp, k0, sr)); S.st_v1 = load8(ROW(Vp, k0, 32 + sr)); S.st_k0 = load8(ROW(Kp, k0, sr)); S.st_k1 = load8(ROW(Kp, k0, 32 + sr)); } while (0)
; #define SWRITE_HV(bf) do { *(bf16x8*)(V_lds + (bf) * SHM_V + vst0) = S.st_v0; *(bf16x8*)(V_lds + (bf) * SHM_V + vst1) = S.st_v1; } while (0)
; #define SWRITE_H(bf) do { SWRITE_HV(bf); SWRITE_HK(bf); } while (0)
; #define MASKT(P0_, P1_, t) do { if (KBASE(t) > (qlo | 63)) { const float NEG_ = -__builtin_inff(); _Pragma("unroll") for (int r_ = 0; r_ < 16; ++r_) { P0_[r_] = NEG_; P1_[r_] = NEG_; } } } while (0)
; template <int VB>
; __device__ __forceinline__ void pv_tile(f32x16* o, int vb0, bf16x8 pa0, bf16x8 pa1, bf16x8 pa2, bf16x8 pa3) {
;     ...
;     PV_D0(0); PV_D0(1); PV_D0(2); PV_D0(3);
;     ...
; }
; __device__ __forceinline__ void attn_block(const BlockRef& cur, const BlockRef& nxt, char* lds, Seam& S) {
;     ...
;     constexpr int NQL = 8;
;     ...
;     f32x16 pA0, pA1, pB0, pB1; float mnA, mnB, alA, alB; bf16x8 pa0, pa1, pa2, pa3;
;     SWRITE_HV(0); SBAR();
;     if (NT > 1) { SLOAD_H(Kh, Vh, KBASE(1)); }
;     SBAR(); qkt<0>(pA0, pA1, K_lds, r32, hi, S.qr);
;     MASKT(pA0, pA1, 0); partialSM(pA0, pA1, m_reg, mnA, alA);
;     if (NT > 1) { VMW(); SWRITE_H(1); }
;     __syncthreads();
	s_nop 0
	v_mfma_f32_32x32x16_bf16 v[0:15], v[96:99], v[238:241], v[0:15]
	ds_read_b64_tr_b16 v[112:113], v225 offset:0x200
	ds_read_b64_tr_b16 v[114:115], v225 offset:0xa00
	v_mfma_f32_32x32x16_bf16 v[0:15], v[100:103], v[242:245], v[0:15]
	ds_read_b64_tr_b16 v[116:117], v225 offset:0x1200
	ds_read_b64_tr_b16 v[118:119], v225 offset:0x1a00
	v_mfma_f32_32x32x16_bf16 v[0:15], v[104:107], v[246:249], v[0:15]
	ds_read_b64_tr_b16 v[120:121], v225 offset:0x2200
	ds_read_b64_tr_b16 v[122:123], v225 offset:0x2a00
	v_mfma_f32_32x32x16_bf16 v[0:15], v[108:111], v[250:253], v[0:15]
	ds_read_b64_tr_b16 v[124:125], v225 offset:0x3200
	ds_read_b64_tr_b16 v[126:127], v225 offset:0x3a00
	s_waitcnt lgkmcnt(0)
	v_mfma_f32_32x32x16_bf16 v[48:63], v[96:99], v[112:115], v[48:63]
	ds_read_b64_tr_b16 v[112:113], v225 offset:0x400
	ds_read_b64_tr_b16 v[114:115], v225 offset:0xc00
	v_mfma_f32_32x32x16_bf16 v[48:63], v[100:103], v[116:119], v[48:63]
	ds_read_b64_tr_b16 v[116:117], v225 offset:0x1400
	ds_read_b64_tr_b16 v[118:119], v225 offset:0x1c00
	v_mfma_f32_32x32x16_bf16 v[48:63], v[104:107], v[120:123], v[48:63]
	ds_read_b64_tr_b16 v[120:121], v225 offset:0x2400
	ds_read_b64_tr_b16 v[122:123], v225 offset:0x2c00
	v_mfma_f32_32x32x16_bf16 v[48:63], v[108:111], v[124:127], v[48:63]
	ds_read_b64_tr_b16 v[124:125], v225 offset:0x3400
	ds_read_b64_tr_b16 v[126:127], v225 offset:0x3c00
	s_waitcnt lgkmcnt(0)
	v_mfma_f32_32x32x16_bf16 v[32:47], v[96:99], v[112:115], v[32:47]
	ds_read_b64_tr_b16 v[112:113], v225 offset:0x600
	ds_read_b64_tr_b16 v[114:115], v225 offset:0xe00
	v_mfma_f32_32x32x16_bf16 v[32:47], v[100:103], v[116:119], v[32:47]
	ds_read_b64_tr_b16 v[116:117], v225 offset:0x1600
	ds_read_b64_tr_b16 v[118:119], v225 offset:0x1e00
	v_mfma_f32_32x32x16_bf16 v[32:47], v[104:107], v[120:123], v[32:47]
	ds_read_b64_tr_b16 v[120:121], v225 offset:0x2600
	ds_read_b64_tr_b16 v[122:123], v225 offset:0x2e00
	v_mfma_f32_32x32x16_bf16 v[32:47], v[108:111], v[124:127], v[32:47]
	ds_read_b64_tr_b16 v[124:125], v225 offset:0x3600
	ds_read_b64_tr_b16 v[126:127], v225 offset:0x3e00
	s_waitcnt lgkmcnt(0)
	s_waitcnt vmcnt(0)
	ds_write_b128 v231, v[160:163] offset:16384
	ds_write_b128 v232, v[164:167] offset:16384
	ds_write_b128 v226, v[168:171] offset:32768
	ds_write_b128 v226, v[172:175] offset:40960
	s_sub_i32 s40, s50, 64
	s_cmp_gt_i32 s40, s49
	s_cbranch_scc0 .Lmy_nomask1
	v_mov_b32_e32 v64, v220
	v_mov_b32_e32 v65, v220
	v_mov_b32_e32 v66, v220
	v_mov_b32_e32 v67, v220
	v_mov_b32_e32 v68, v220
	v_mov_b32_e32 v69, v220
	v_mov_b32_e32 v70, v220
	v_mov_b32_e32 v71, v220
	v_mov_b32_e32 v72, v220
	v_mov_b32_e32 v73, v220
	v_mov_b32_e32 v74, v220
	v_mov_b32_e32 v75, v220
	v_mov_b32_e32 v76, v220
	v_mov_b32_e32 v77, v220
	v_mov_b32_e32 v78, v220
	v_mov_b32_e32 v79, v220
	v_mov_b32_e32 v80, v220
	v_mov_b32_e32 v81, v220
	v_mov_b32_e32 v82, v220
	v_mov_b32_e32 v83, v220
	v_mov_b32_e32 v84, v220
	v_mov_b32_e32 v85, v220
	v_mov_b32_e32 v86, v220
	v_mov_b32_e32 v87, v220
	v_mov_b32_e32 v88, v220
	v_mov_b32_e32 v89, v220
	v_mov_b32_e32 v90, v220
	v_mov_b32_e32 v91, v220
	v_mov_b32_e32 v92, v220
	v_mov_b32_e32 v93, v220
	v_mov_b32_e32 v94, v220
	v_mov_b32_e32 v95, v220
.Lmy_nomask1:
	v_mfma_f32_32x32x16_bf16 v[16:31], v[96:99], v[112:115], v[16:31]
	v_mov_b32_e32 v97, v81
	v_mov_b32_e32 v98, v80
	v_mov_b32_e32 v96, v82
	v_mov_b32_e32 v81, v78
	v_mov_b32_e32 v82, v77
	v_max_f32_e32 v77, v97, v97
	v_max_f32_e32 v78, v98, v98
	v_max_f32_e32 v77, v78, v77
	v_max3_f32 v77, v77, v96, v83
	v_max3_f32 v77, v77, v84, v85
	v_max3_f32 v77, v77, v86, v87
	v_max3_f32 v77, v77, v88, v89
	v_max3_f32 v77, v77, v90, v91
	v_max3_f32 v77, v77, v92, v93
	v_max3_f32 v77, v77, v94, v95
	v_mfma_f32_32x32x16_bf16 v[16:31], v[100:103], v[116:119], v[16:31]
	v_max3_f32 v77, v77, v64, v65
	v_max3_f32 v77, v77, v66, v67
	v_max3_f32 v77, v77, v68, v69
	v_max3_f32 v77, v77, v70, v71
	v_max3_f32 v77, v77, v72, v73
	v_max3_f32 v77, v77, v74, v75
	v_mov_b32_e32 v80, v79
	v_max3_f32 v77, v77, v76, v82
	v_max3_f32 v77, v77, v81, v80
	v_mfma_f32_32x32x16_bf16 v[16:31], v[104:107], v[120:123], v[16:31]
	v_mov_b32_e32 v78, v77
	s_nop 1
	v_permlane32_swap_b32_e32 v77, v78
	v_max_f32_e32 v78, v78, v78
	v_max_f32_e32 v77, v77, v77
	v_max_f32_e32 v77, v77, v78
	v_sub_f32_e32 v78, v77, v176
	v_mul_f32_e32 v78, 0x3db504f3, v78
	v_cmp_ge_f32_e32 vcc, s67, v78
	v_max_f32_e32 v78, v176, v176
	v_max_f32_e32 v77, v78, v77
	v_mfma_f32_32x32x16_bf16 v[16:31], v[108:111], v[124:127], v[16:31]
	v_sub_f32_e32 v78, v176, v77
	v_mul_f32_e32 v78, 0x3e0293ee, v78
	v_exp_f32_e32 v78, v78
	s_cmp_eq_u64 vcc, exec
	s_cselect_b64 s[40:41], -1, 0
	v_cndmask_b32_e64 v213, v78, 1.0, s[40:41]
	v_cmp_gt_f32_e32 vcc, 1.0, v213
	s_cbranch_vccz .LBB0_324
	s_and_saveexec_b64 s[42:43], s[38:39]
	ds_write_b32 v227, v213 offset:128
	s_or_b64 exec, exec, s[42:43]
	s_waitcnt lgkmcnt(0)
	v_add_u32_e32 v78, s69, v200
	ds_read_b128 v[100:103], v78 offset:224
	ds_read_b128 v[104:107], v78 offset:192
	ds_read_b128 v[108:111], v78 offset:160
	ds_read_b128 v[112:115], v78 offset:128
	s_waitcnt lgkmcnt(3)
	v_pk_mul_f32 v[12:13], v[12:13], v[100:101]
	s_waitcnt lgkmcnt(2)
	v_pk_mul_f32 v[8:9], v[8:9], v[104:105]
	s_waitcnt lgkmcnt(1)
	v_pk_mul_f32 v[4:5], v[4:5], v[108:109]
	v_pk_mul_f32 v[14:15], v[14:15], v[102:103]
	v_pk_mul_f32 v[10:11], v[10:11], v[106:107]
	v_pk_mul_f32 v[6:7], v[6:7], v[110:111]
	s_waitcnt lgkmcnt(0)
	v_pk_mul_f32 v[2:3], v[2:3], v[114:115]
	v_pk_mul_f32 v[0:1], v[0:1], v[112:113]
	v_pk_mul_f32 v[60:61], v[60:61], v[100:101]
	v_pk_mul_f32 v[56:57], v[56:57], v[104:105]
	v_pk_mul_f32 v[52:53], v[52:53], v[108:109]
	v_pk_mul_f32 v[62:63], v[62:63], v[102:103]
	v_pk_mul_f32 v[58:59], v[58:59], v[106:107]
	v_pk_mul_f32 v[54:55], v[54:55], v[110:111]
	v_pk_mul_f32 v[50:51], v[50:51], v[114:115]
	v_pk_mul_f32 v[48:49], v[48:49], v[112:113]
	v_pk_mul_f32 v[44:45], v[44:45], v[100:101]
	v_pk_mul_f32 v[40:41], v[40:41], v[104:105]
	v_pk_mul_f32 v[36:37], v[36:37], v[108:109]
	v_pk_mul_f32 v[46:47], v[46:47], v[102:103]
	v_pk_mul_f32 v[42:43], v[42:43], v[106:107]
	v_pk_mul_f32 v[38:39], v[38:39], v[110:111]
	v_pk_mul_f32 v[34:35], v[34:35], v[114:115]
	v_pk_mul_f32 v[32:33], v[32:33], v[112:113]
	v_pk_mul_f32 v[28:29], v[28:29], v[100:101]
	v_pk_mul_f32 v[24:25], v[24:25], v[104:105]
	v_pk_mul_f32 v[20:21], v[20:21], v[108:109]
	v_pk_mul_f32 v[30:31], v[30:31], v[102:103]
	v_pk_mul_f32 v[26:27], v[26:27], v[106:107]
	v_pk_mul_f32 v[22:23], v[22:23], v[110:111]
	v_pk_mul_f32 v[18:19], v[18:19], v[114:115]
	v_pk_mul_f32 v[16:17], v[16:17], v[112:113]
; __device__ __forceinline__ void partialSM(f32x16& p0, f32x16& p1, float& m_reg, float& mn, float& alpha) {
;     float pmax = p0[0]; for (int r = 1; r < 16; ++r) pmax = fmaxf(pmax, p0[r]); for (int r = 0; r < 16; ++r) pmax = fmaxf(pmax, p1[r]);
;     { auto rr = __builtin_amdgcn_permlane32_swap(__float_as_uint(pmax), __float_as_uint(pmax), false, false);
;       pmax = fmaxf(__uint_as_float(rr[0]), __uint_as_float(rr[1])); }
;     constexpr float C2 = 1.4426950408889634f * SCALE;
;     if (__builtin_expect(__all((pmax - m_reg) * SCALE <= THR), 1)) { mn = m_reg; alpha = 1.f; }
;     else { mn = fmaxf(m_reg, pmax); alpha = __builtin_amdgcn_exp2f((m_reg - mn) * C2); m_reg = mn; }
;     const float mnL = -mn * C2;
;     for (int r = 0; r < 16; ++r) p0[r] = fmaf(p0[r], C2, mnL); for (int r = 0; r < 16; ++r) p1[r] = fmaf(p1[r], C2, mnL);
;     for (int r = 0; r < 16; ++r) p0[r] = __builtin_amdgcn_exp2f(p0[r]);
; }
; __device__ __forceinline__ void finishSM(f32x16& p0, f32x16& p1, float alpha, float& l_reg, bf16x8& pa0, bf16x8& pa1, bf16x8& pa2, bf16x8& pa3) {
;     for (int r = 0; r < 16; ++r) p1[r] = __builtin_amdgcn_exp2f(p1[r]);
;     float ps = 0; for (int r = 0; r < 16; ++r) ps += p0[r]; for (int r = 0; r < 16; ++r) ps += p1[r];
;     { auto rr = __builtin_amdgcn_permlane32_swap(__float_as_uint(ps), __float_as_uint(ps), false, false);
;       ps = __uint_as_float(rr[0]) + __uint_as_float(rr[1]); }
;     l_reg = l_reg * alpha + ps;
;     ...
;     PK4(p0, 0, pa0); PK4(p0, 8, pa1); PK4(p1, 0, pa2); PK4(p1, 8, pa3);
;     ...
; }
; template <int KB>
; __device__ __forceinline__ void qkt(f32x16& p0, f32x16& p1, const char* K_lds, int r32, int hi, const bf16x8* qr) {
;     p0 = f32x16{}; p1 = f32x16{};
;     const char* kb[4];
; #pragma unroll
;     for (int dd = 0; dd < 4; ++dd) kb[dd] = K_lds + KB * SHM_K + KSWZ(r32, (dd * 16 + hi * 8) * 2);
; #pragma unroll
;     for (int d0 = 0; d0 < 8; ++d0) { const char* a = kb[d0 & 3] + (d0 >> 2) * 128;
;         bf16x8 b0 = *reinterpret_cast<const bf16x8*>(a);
;         bf16x8 b1 = *reinterpret_cast<const bf16x8*>(a + 32 * 256);
;         p0 = __builtin_amdgcn_mfma_f32_32x32x16_bf16(b0, qr[d0], p0, 0, 0, 0);
;         p1 = __builtin_amdgcn_mfma_f32_32x32x16_bf16(b1, qr[d0], p1, 0, 0, 0); }
; }
.LBB0_324:
	v_cndmask_b32_e64 v235, v77, v176, s[40:41]
	v_mul_f32_e32 v176, 0xbe0293ee, v235
	v_fmamk_f32 v77, v98, 0x3e0293ee, v176
	v_fmamk_f32 v78, v97, 0x3e0293ee, v176
	v_fmamk_f32 v79, v96, 0x3e0293ee, v176
	v_fmamk_f32 v96, v83, 0x3e0293ee, v176
	v_fmamk_f32 v97, v84, 0x3e0293ee, v176
	v_fmamk_f32 v98, v85, 0x3e0293ee, v176
	v_fmamk_f32 v99, v86, 0x3e0293ee, v176
	v_fmamk_f32 v100, v87, 0x3e0293ee, v176
	v_fmamk_f32 v101, v88, 0x3e0293ee, v176
	v_fmamk_f32 v102, v89, 0x3e0293ee, v176
	v_fmamk_f32 v103, v90, 0x3e0293ee, v176
	v_fmamk_f32 v104, v91, 0x3e0293ee, v176
	v_fmamk_f32 v105, v92, 0x3e0293ee, v176
	v_fmamk_f32 v106, v93, 0x3e0293ee, v176
	v_fmamk_f32 v107, v94, 0x3e0293ee, v176
	v_fmamk_f32 v108, v95, 0x3e0293ee, v176
	v_fmamk_f32 v83, v64, 0x3e0293ee, v176
	v_fmamk_f32 v84, v65, 0x3e0293ee, v176
	v_fmamk_f32 v93, v66, 0x3e0293ee, v176
	v_fmamk_f32 v94, v67, 0x3e0293ee, v176
	v_fmamk_f32 v95, v68, 0x3e0293ee, v176
	v_fmamk_f32 v85, v69, 0x3e0293ee, v176
	v_fmamk_f32 v86, v70, 0x3e0293ee, v176
	v_fmamk_f32 v87, v71, 0x3e0293ee, v176
	v_fmamk_f32 v88, v72, 0x3e0293ee, v176
	v_fmamk_f32 v89, v73, 0x3e0293ee, v176
	v_fmamk_f32 v90, v74, 0x3e0293ee, v176
	v_fmamk_f32 v91, v75, 0x3e0293ee, v176
	v_fmamk_f32 v92, v76, 0x3e0293ee, v176
	v_exp_f32_e32 v64, v77
	v_exp_f32_e32 v65, v78
	v_exp_f32_e32 v66, v79
	v_exp_f32_e32 v67, v96
	v_exp_f32_e32 v68, v97
	v_exp_f32_e32 v69, v98
	v_exp_f32_e32 v70, v99
	v_exp_f32_e32 v71, v100
	v_exp_f32_e32 v72, v101
	v_exp_f32_e32 v73, v102
	v_exp_f32_e32 v74, v103
	v_exp_f32_e32 v75, v104
	v_exp_f32_e32 v76, v105
	v_exp_f32_e32 v77, v106
	v_exp_f32_e32 v78, v107
	v_exp_f32_e32 v79, v108
	v_fmamk_f32 v177, v82, 0x3e0293ee, v176
	v_fmamk_f32 v178, v81, 0x3e0293ee, v176
	v_fmac_f32_e32 v176, 0x3e0293ee, v80
	s_waitcnt lgkmcnt(0)
	s_barrier
	v_xor_b32_e32 v250, 0x80, v201
	v_xor_b32_e32 v251, 0x80, v230
	v_xor_b32_e32 v252, 0x80, v229
	v_xor_b32_e32 v253, 0x80, v207
	ds_read_b128 v[96:99], v201 offset:32768
	ds_read_b128 v[100:103], v201 offset:40960
	ds_read_b128 v[180:183], v230 offset:32768
	ds_read_b128 v[184:187], v230 offset:40960
	v_exp_f32_e32 v81, v84
	v_exp_f32_e32 v84, v95
	s_waitcnt lgkmcnt(3)
	v_mfma_f32_32x32x16_bf16 v[112:127], v[96:99], v[156:159], 0
	v_exp_f32_e32 v95, v176
	v_add_f32_e32 v176, 0, v64
	v_add_f32_e32 v176, v65, v176
	v_add_f32_e32 v176, v66, v176
	v_add_f32_e32 v176, v67, v176
	v_add_f32_e32 v176, v68, v176
	v_add_f32_e32 v176, v69, v176
	s_waitcnt lgkmcnt(2)
	v_mfma_f32_32x32x16_bf16 v[96:111], v[100:103], v[156:159], 0
	v_add_f32_e32 v176, v70, v176
	v_add_f32_e32 v176, v71, v176
	v_add_f32_e32 v176, v72, v176
	v_add_f32_e32 v176, v73, v176
	v_add_f32_e32 v176, v74, v176
	v_add_f32_e32 v176, v75, v176
	v_exp_f32_e32 v80, v83
	s_waitcnt lgkmcnt(1)
	v_mfma_f32_32x32x16_bf16 v[112:127], v[180:183], v[152:155], v[112:127]
	v_add_f32_e32 v176, v76, v176
	v_add_f32_e32 v176, v77, v176
	v_exp_f32_e32 v82, v93
	v_add_f32_e32 v176, v78, v176
	v_exp_f32_e32 v83, v94
	v_add_f32_e32 v176, v79, v176
	v_add_f32_e32 v176, v80, v176
	s_waitcnt lgkmcnt(0)
	v_mfma_f32_32x32x16_bf16 v[96:111], v[184:187], v[152:155], v[96:111]
	ds_read_b128 v[180:183], v229 offset:32768
	ds_read_b128 v[184:187], v229 offset:40960
	v_exp_f32_e32 v85, v85
	v_add_f32_e32 v176, v81, v176
	v_exp_f32_e32 v86, v86
	v_add_f32_e32 v176, v82, v176
	v_exp_f32_e32 v87, v87
	v_add_f32_e32 v176, v83, v176
	s_waitcnt lgkmcnt(1)
	v_mfma_f32_32x32x16_bf16 v[112:127], v[180:183], v[148:151], v[112:127]
	v_exp_f32_e32 v88, v88
	v_add_f32_e32 v176, v84, v176
	v_exp_f32_e32 v89, v89
	v_add_f32_e32 v176, v85, v176
	v_exp_f32_e32 v90, v90
	v_add_f32_e32 v176, v86, v176
	v_exp_f32_e32 v91, v91
	s_waitcnt lgkmcnt(0)
	v_mfma_f32_32x32x16_bf16 v[96:111], v[184:187], v[148:151], v[96:111]
	ds_read_b128 v[180:183], v207 offset:32768
	ds_read_b128 v[184:187], v207 offset:40960
	v_add_f32_e32 v176, v87, v176
	v_exp_f32_e32 v92, v92
	v_add_f32_e32 v176, v88, v176
	v_exp_f32_e32 v93, v177
	v_add_f32_e32 v176, v89, v176
	v_exp_f32_e32 v94, v178
	s_waitcnt lgkmcnt(1)
	v_mfma_f32_32x32x16_bf16 v[112:127], v[180:183], v[144:147], v[112:127]
	v_add_f32_e32 v176, v90, v176
	v_add_f32_e32 v176, v91, v176
	v_add_f32_e32 v176, v92, v176
	v_add_f32_e32 v176, v93, v176
	v_add_f32_e32 v176, v94, v176
	v_add_f32_e32 v236, v95, v176
	v_mov_b32_e32 v237, v236
	s_waitcnt lgkmcnt(0)
	v_mfma_f32_32x32x16_bf16 v[96:111], v[184:187], v[144:147], v[96:111]
	ds_read_b128 v[180:183], v250 offset:32768
	ds_read_b128 v[184:187], v250 offset:40960
	v_cvt_pk_bf16_f32 v176, v64, v65
	v_cvt_pk_bf16_f32 v177, v66, v67
	v_cvt_pk_bf16_f32 v178, v68, v69
	v_cvt_pk_bf16_f32 v179, v70, v71
	v_cvt_pk_bf16_f32 v188, v88, v89
	v_cvt_pk_bf16_f32 v189, v90, v91
	s_waitcnt lgkmcnt(1)
	v_mfma_f32_32x32x16_bf16 v[112:127], v[180:183], v[140:143], v[112:127]
	v_cvt_pk_bf16_f32 v190, v92, v93
	v_cvt_pk_bf16_f32 v191, v94, v95
	v_permlane32_swap_b32_e32 v236, v237
	v_permlane32_swap_b32_e32 v176, v178
	v_permlane32_swap_b32_e32 v177, v179
	s_waitcnt lgkmcnt(0)
	v_mfma_f32_32x32x16_bf16 v[96:111], v[184:187], v[140:143], v[96:111]
	ds_read_b128 v[180:183], v251 offset:32768
	ds_read_b128 v[184:187], v251 offset:40960
	v_permlane32_swap_b32_e32 v188, v190
	v_permlane32_swap_b32_e32 v189, v191
	s_waitcnt lgkmcnt(1)
	v_mfma_f32_32x32x16_bf16 v[112:127], v[180:183], v[136:139], v[112:127]
	s_waitcnt lgkmcnt(0)
	v_mfma_f32_32x32x16_bf16 v[96:111], v[184:187], v[136:139], v[96:111]
	ds_read_b128 v[180:183], v252 offset:32768
	ds_read_b128 v[184:187], v252 offset:40960
	s_waitcnt lgkmcnt(1)
	v_mfma_f32_32x32x16_bf16 v[112:127], v[180:183], v[132:135], v[112:127]
	s_waitcnt lgkmcnt(0)
	v_mfma_f32_32x32x16_bf16 v[96:111], v[184:187], v[132:135], v[96:111]
	ds_read_b128 v[180:183], v253 offset:32768
	ds_read_b128 v[184:187], v253 offset:40960
	ds_read_b64_tr_b16 v[238:239], v225 offset:0x4000
	ds_read_b64_tr_b16 v[240:241], v225 offset:0x4800
	ds_read_b64_tr_b16 v[242:243], v225 offset:0x5000
	ds_read_b64_tr_b16 v[244:245], v225 offset:0x5800
	ds_read_b64_tr_b16 v[246:247], v225 offset:0x6000
	ds_read_b64_tr_b16 v[248:249], v225 offset:0x6800
	ds_read_b64_tr_b16 v[250:251], v225 offset:0x7000
	ds_read_b64_tr_b16 v[252:253], v225 offset:0x7800
	s_waitcnt lgkmcnt(9)
	v_mfma_f32_32x32x16_bf16 v[112:127], v[180:183], v[128:131], v[112:127]
	v_cvt_pk_bf16_f32 v180, v72, v73
	v_cvt_pk_bf16_f32 v181, v74, v75
	v_cvt_pk_bf16_f32 v182, v76, v77
	v_cvt_pk_bf16_f32 v183, v78, v79
	s_nop 0
	v_permlane32_swap_b32_e32 v180, v182
	v_permlane32_swap_b32_e32 v181, v183
	s_waitcnt lgkmcnt(8)
	v_mfma_f32_32x32x16_bf16 v[96:111], v[184:187], v[128:131], v[96:111]
	v_cvt_pk_bf16_f32 v184, v80, v81
	v_cvt_pk_bf16_f32 v185, v82, v83
	v_cvt_pk_bf16_f32 v186, v84, v85
	v_cvt_pk_bf16_f32 v187, v86, v87
	s_nop 0
	v_permlane32_swap_b32_e32 v184, v186
	v_permlane32_swap_b32_e32 v185, v187
	s_add_i32 s40, s80, 1
	s_cmp_lt_u32 s40, s79
	s_cselect_b64 s[42:43], -1, 0
	s_cmp_ge_u32 s40, s79
	s_cbranch_scc1 .LBB0_326
; template <int VB>
; __device__ __forceinline__ void pv_tile(f32x16* o, int vb0, bf16x8 pa0, bf16x8 pa1, bf16x8 pa2, bf16x8 pa3) {
;     ...
;     PV_D0(0); PV_D0(1); PV_D0(2); PV_D0(3);
;     ...
; }
	v_add_u32_e32 v160, 64, v212
	v_add_u32_e32 v162, 0x60, v212
	v_ashrrev_i32_e32 v161, 31, v160
	v_ashrrev_i32_e32 v163, 31, v162
	v_lshlrev_b64 v[168:169], 8, v[160:161]
	v_lshlrev_b64 v[170:171], 8, v[162:163]
	v_lshl_add_u64 v[160:161], v[208:209], 0, v[168:169]
	v_lshl_add_u64 v[164:165], v[208:209], 0, v[170:171]
	v_lshl_add_u64 v[168:169], v[210:211], 0, v[168:169]
	v_lshl_add_u64 v[172:173], v[210:211], 0, v[170:171]
	global_load_dwordx4 v[160:163], v[160:161], off
	s_nop 0
	global_load_dwordx4 v[164:167], v[164:165], off
	s_nop 0
	global_load_dwordx4 v[168:171], v[168:169], off
	s_nop 0
	global_load_dwordx4 v[172:175], v[172:173], off
.LBB0_326:
	s_waitcnt lgkmcnt(0)
	s_nop 0
	v_mfma_f32_32x32x16_bf16 v[0:15], v[176:179], v[238:241], v[0:15]
	ds_read_b64_tr_b16 v[238:239], v225 offset:0x4200
	ds_read_b64_tr_b16 v[240:241], v225 offset:0x4a00
	v_mfma_f32_32x32x16_bf16 v[0:15], v[180:183], v[242:245], v[0:15]
	ds_read_b64_tr_b16 v[242:243], v225 offset:0x5200
	ds_read_b64_tr_b16 v[244:245], v225 offset:0x5a00
	v_mfma_f32_32x32x16_bf16 v[0:15], v[184:187], v[246:249], v[0:15]
	ds_read_b64_tr_b16 v[246:247], v225 offset:0x6200
	ds_read_b64_tr_b16 v[248:249], v225 offset:0x6a00
	v_mfma_f32_32x32x16_bf16 v[0:15], v[188:191], v[250:253], v[0:15]
	ds_read_b64_tr_b16 v[250:251], v225 offset:0x7200
	ds_read_b64_tr_b16 v[252:253], v225 offset:0x7a00
	s_waitcnt lgkmcnt(0)
	v_mfma_f32_32x32x16_bf16 v[48:63], v[176:179], v[238:241], v[48:63]
	ds_read_b64_tr_b16 v[238:239], v225 offset:0x4400
	ds_read_b64_tr_b16 v[240:241], v225 offset:0x4c00
	v_mfma_f32_32x32x16_bf16 v[48:63], v[180:183], v[242:245], v[48:63]
	ds_read_b64_tr_b16 v[242:243], v225 offset:0x5400
	ds_read_b64_tr_b16 v[244:245], v225 offset:0x5c00
	v_mfma_f32_32x32x16_bf16 v[48:63], v[184:187], v[246:249], v[48:63]
	ds_read_b64_tr_b16 v[246:247], v225 offset:0x6400
	ds_read_b64_tr_b16 v[248:249], v225 offset:0x6c00
	v_mfma_f32_32x32x16_bf16 v[48:63], v[188:191], v[250:253], v[48:63]
	ds_read_b64_tr_b16 v[250:251], v225 offset:0x7400
	ds_read_b64_tr_b16 v[252:253], v225 offset:0x7c00
	s_waitcnt lgkmcnt(0)
	v_mfma_f32_32x32x16_bf16 v[32:47], v[176:179], v[238:241], v[32:47]
	ds_read_b64_tr_b16 v[238:239], v225 offset:0x4600
	ds_read_b64_tr_b16 v[240:241], v225 offset:0x4e00
	v_mfma_f32_32x32x16_bf16 v[32:47], v[180:183], v[242:245], v[32:47]
	ds_read_b64_tr_b16 v[242:243], v225 offset:0x5600
	ds_read_b64_tr_b16 v[244:245], v225 offset:0x5e00
	v_mfma_f32_32x32x16_bf16 v[32:47], v[184:187], v[246:249], v[32:47]
	ds_read_b64_tr_b16 v[246:247], v225 offset:0x6600
	ds_read_b64_tr_b16 v[248:249], v225 offset:0x6e00
	v_mfma_f32_32x32x16_bf16 v[32:47], v[188:191], v[250:253], v[32:47]
	ds_read_b64_tr_b16 v[250:251], v225 offset:0x7600
	ds_read_b64_tr_b16 v[252:253], v225 offset:0x7e00
	s_waitcnt lgkmcnt(0)
	s_and_b64 vcc, exec, s[42:43]
	s_cbranch_vccz .Lmy_skip_w2
	s_waitcnt vmcnt(0)
	ds_write_b128 v231, v[160:163]
	ds_write_b128 v232, v[164:167]
	ds_write_b128 v226, v[168:171] offset:49152
	ds_write_b128 v226, v[172:175] offset:57344
.Lmy_skip_w2:
	v_mfma_f32_32x32x16_bf16 v[16:31], v[176:179], v[238:241], v[16:31]
	s_cmp_gt_i32 s50, s49
	s_cbranch_scc0 .Lmy_nomask2
	v_mov_b32_e32 v96, v220
	v_mov_b32_e32 v97, v220
	v_mov_b32_e32 v98, v220
	v_mov_b32_e32 v99, v220
	v_mov_b32_e32 v100, v220
	v_mov_b32_e32 v101, v220
	v_mov_b32_e32 v102, v220
	v_mov_b32_e32 v103, v220
	v_mov_b32_e32 v104, v220
	v_mov_b32_e32 v105, v220
	v_mov_b32_e32 v106, v220
	v_mov_b32_e32 v107, v220
	v_mov_b32_e32 v108, v220
	v_mov_b32_e32 v109, v220
	v_mov_b32_e32 v110, v220
	v_mov_b32_e32 v111, v220
	v_mov_b32_e32 v112, v220
	v_mov_b32_e32 v113, v220
	v_mov_b32_e32 v114, v220
	v_mov_b32_e32 v115, v220
	v_mov_b32_e32 v116, v220
	v_mov_b32_e32 v117, v220
	v_mov_b32_e32 v118, v220
	v_mov_b32_e32 v119, v220
	v_mov_b32_e32 v120, v220
	v_mov_b32_e32 v121, v220
	v_mov_b32_e32 v122, v220
	v_mov_b32_e32 v123, v220
	v_mov_b32_e32 v124, v220
	v_mov_b32_e32 v125, v220
	v_mov_b32_e32 v126, v220
	v_mov_b32_e32 v127, v220
; #define SBAR() __builtin_amdgcn_sched_barrier(0)
; #define VMW() asm volatile("s_waitcnt vmcnt(0)" ::: "memory")
; #define SLOAD_H(Kp, Vp, k0) do { S.st_v0 = load8(ROW(Vp, k0, sr)); S.st_v1 = load8(ROW(Vp, k0, 32 + sr)); S.st_k0 = load8(ROW(Kp, k0, sr)); S.st_k1 = load8(ROW(Kp, k0, 32 + sr)); } while (0)
; #define SWRITE_HV(bf) do { *(bf16x8*)(V_lds + (bf) * SHM_V + vst0) = S.st_v0; *(bf16x8*)(V_lds + (bf) * SHM_V + vst1) = S.st_v1; } while (0)
; #define SWRITE_H(bf) do { SWRITE_HV(bf); SWRITE_HK(bf); } while (0)
; #define MASKT(P0_, P1_, t) do { if (KBASE(t) > (qlo | 63)) { const float NEG_ = -__builtin_inff(); _Pragma("unroll") for (int r_ = 0; r_ < 16; ++r_) { P0_[r_] = NEG_; P1_[r_] = NEG_; } } } while (0)
; __device__ __forceinline__ void partialSM(f32x16& p0, f32x16& p1, float& m_reg, float& mn, float& alpha) {
;     float pmax = p0[0]; for (int r = 1; r < 16; ++r) pmax = fmaxf(pmax, p0[r]); for (int r = 0; r < 16; ++r) pmax = fmaxf(pmax, p1[r]);
;     { auto rr = __builtin_amdgcn_permlane32_swap(__float_as_uint(pmax), __float_as_uint(pmax), false, false);
;       pmax = fmaxf(__uint_as_float(rr[0]), __uint_as_float(rr[1])); }
;     constexpr float C2 = 1.4426950408889634f * SCALE;
;     if (__builtin_expect(__all((pmax - m_reg) * SCALE <= THR), 1)) { mn = m_reg; alpha = 1.f; }
;     else { mn = fmaxf(m_reg, pmax); alpha = __builtin_amdgcn_exp2f((m_reg - mn) * C2); m_reg = mn; }
; __device__ __forceinline__ void attn_block(const BlockRef& cur, const BlockRef& nxt, char* lds, Seam& S) {
;     ...
;     constexpr int NQL = 8;
;     ...
;     f32x16 pA0, pA1, pB0, pB1; float mnA, mnB, alA, alB; bf16x8 pa0, pa1, pa2, pa3;
;     SWRITE_HV(0); SBAR();
;     if (NT > 1) { SLOAD_H(Kh, Vh, KBASE(1)); }
;     SBAR(); qkt<0>(pA0, pA1, K_lds, r32, hi, S.qr);
;     MASKT(pA0, pA1, 0); partialSM(pA0, pA1, m_reg, mnA, alA);
;     if (NT > 1) { VMW(); SWRITE_H(1); }
;     __syncthreads();
;     ...
;     for (int t = 1; t + 1 < NT; t += 2) {
;         HALF_STEP(pB0, pB1, mnB, alB, pA0, pA1, alA, t, 1, 0, 0);
;         HALF_STEP(pA0, pA1, mnA, alA, pB0, pB1, alB, t + 1, 0, 1, 1);
.Lmy_nomask2:
	v_max_f32_e32 v176, v113, v113
	v_max_f32_e32 v177, v112, v112
	v_max_f32_e32 v176, v177, v176
	v_mfma_f32_32x32x16_bf16 v[16:31], v[180:183], v[242:245], v[16:31]
	v_max3_f32 v176, v176, v114, v115
	v_max3_f32 v176, v176, v116, v117
	v_max3_f32 v176, v176, v118, v119
	v_max3_f32 v176, v176, v120, v121
	v_max3_f32 v176, v176, v122, v123
	v_max3_f32 v176, v176, v124, v125
	v_max3_f32 v176, v176, v126, v127
	v_max3_f32 v176, v176, v96, v97
	v_mfma_f32_32x32x16_bf16 v[16:31], v[184:187], v[246:249], v[16:31]
	v_max3_f32 v176, v176, v98, v99
	v_max3_f32 v176, v176, v100, v101
	v_max3_f32 v176, v176, v102, v103
	v_max3_f32 v176, v176, v104, v105
	v_max3_f32 v176, v176, v106, v107
	v_max3_f32 v176, v176, v108, v109
	v_max3_f32 v176, v176, v110, v111
	v_mov_b32_e32 v177, v176
	v_mfma_f32_32x32x16_bf16 v[16:31], v[188:191], v[250:253], v[16:31]
	s_nop 0
	v_permlane32_swap_b32_e32 v176, v177
	v_max_f32_e32 v177, v177, v177
	v_max_f32_e32 v176, v176, v176
	v_max_f32_e32 v176, v176, v177
	v_sub_f32_e32 v177, v176, v235
	v_mul_f32_e32 v177, 0x3db504f3, v177
	v_cmp_ge_f32_e32 vcc, s67, v177
	s_cmp_eq_u64 vcc, exec
	s_cselect_b64 s[40:41], -1, 0
.LBB0_328:
	s_waitcnt vmcnt(3)
	v_max_f32_e32 v160, v235, v235
	v_max_f32_e32 v161, v160, v176
	v_sub_f32_e32 v160, v235, v161
	v_mul_f32_e32 v160, 0x3e0293ee, v160
	v_exp_f32_e32 v160, v160
	s_nop 0
	v_cndmask_b32_e64 v160, v160, 1.0, s[40:41]
	v_cmp_gt_f32_e32 vcc, 1.0, v160
	s_cbranch_vccz .LBB0_332
	s_and_saveexec_b64 s[42:43], s[38:39]
	ds_write_b32 v227, v160 offset:128
	s_or_b64 exec, exec, s[42:43]
	s_waitcnt lgkmcnt(0)
	s_waitcnt vmcnt(0)
	v_add_u32_e32 v174, s69, v200
	ds_read_b128 v[162:165], v174 offset:224
	ds_read_b128 v[166:169], v174 offset:192
	ds_read_b128 v[170:173], v174 offset:160
	ds_read_b128 v[174:177], v174 offset:128
	s_waitcnt lgkmcnt(3)
	v_pk_mul_f32 v[12:13], v[12:13], v[162:163]
	s_waitcnt lgkmcnt(2)
	v_pk_mul_f32 v[8:9], v[8:9], v[166:167]
	s_waitcnt lgkmcnt(1)
	v_pk_mul_f32 v[4:5], v[4:5], v[170:171]
	v_pk_mul_f32 v[14:15], v[14:15], v[164:165]
	v_pk_mul_f32 v[10:11], v[10:11], v[168:169]
	v_pk_mul_f32 v[6:7], v[6:7], v[172:173]
	s_waitcnt lgkmcnt(0)
	v_pk_mul_f32 v[2:3], v[2:3], v[176:177]
	v_pk_mul_f32 v[0:1], v[0:1], v[174:175]
	v_pk_mul_f32 v[60:61], v[60:61], v[162:163]
	v_pk_mul_f32 v[56:57], v[56:57], v[166:167]
	v_pk_mul_f32 v[52:53], v[52:53], v[170:171]
	v_pk_mul_f32 v[62:63], v[62:63], v[164:165]
	v_pk_mul_f32 v[58:59], v[58:59], v[168:169]
	v_pk_mul_f32 v[54:55], v[54:55], v[172:173]
	v_pk_mul_f32 v[50:51], v[50:51], v[176:177]
	v_pk_mul_f32 v[48:49], v[48:49], v[174:175]
	v_pk_mul_f32 v[44:45], v[44:45], v[162:163]
	v_pk_mul_f32 v[40:41], v[40:41], v[166:167]
	v_pk_mul_f32 v[36:37], v[36:37], v[170:171]
	v_pk_mul_f32 v[46:47], v[46:47], v[164:165]
	v_pk_mul_f32 v[42:43], v[42:43], v[168:169]
	v_pk_mul_f32 v[38:39], v[38:39], v[172:173]
	v_pk_mul_f32 v[34:35], v[34:35], v[176:177]
	v_pk_mul_f32 v[32:33], v[32:33], v[174:175]
	v_pk_mul_f32 v[28:29], v[28:29], v[162:163]
	v_pk_mul_f32 v[24:25], v[24:25], v[166:167]
	v_pk_mul_f32 v[20:21], v[20:21], v[170:171]
	v_pk_mul_f32 v[30:31], v[30:31], v[164:165]
	v_pk_mul_f32 v[26:27], v[26:27], v[168:169]
	v_pk_mul_f32 v[22:23], v[22:23], v[172:173]
	v_pk_mul_f32 v[18:19], v[18:19], v[176:177]
	v_pk_mul_f32 v[16:17], v[16:17], v[174:175]

; #define SBAR() __builtin_amdgcn_sched_barrier(0)
; #define SLOAD_H(Kp, Vp, k0) do { S.st_v0 = load8(ROW(Vp, k0, sr)); S.st_v1 = load8(ROW(Vp, k0, 32 + sr)); S.st_k0 = load8(ROW(Kp, k0, sr)); S.st_k1 = load8(ROW(Kp, k0, 32 + sr)); } while (0)
; #define RESC(a) do { if (__any((a) < 1.f)) { if (hi == 0) al_l[r32] = (a); asm volatile("s_waitcnt lgkmcnt(0)" ::: "memory");              \
;                      for (int d_ = 0; d_ < 4; ++d_) for (int r = 0; r < 16; ++r) o[d_][r] *= al_l[crow(r, hi)]; } } while (0)
; template <int KB>
; __device__ __forceinline__ void qkt(f32x16& p0, f32x16& p1, const char* K_lds, int r32, int hi, const bf16x8* qr) {
;     p0 = f32x16{}; p1 = f32x16{};
;     const char* kb[4];
; #pragma unroll
;     for (int dd = 0; dd < 4; ++dd) kb[dd] = K_lds + KB * SHM_K + KSWZ(r32, (dd * 16 + hi * 8) * 2);
; #pragma unroll
;     for (int d0 = 0; d0 < 8; ++d0) { const char* a = kb[d0 & 3] + (d0 >> 2) * 128;
;         bf16x8 b0 = *reinterpret_cast<const bf16x8*>(a);
;         bf16x8 b1 = *reinterpret_cast<const bf16x8*>(a + 32 * 256);
;         p0 = __builtin_amdgcn_mfma_f32_32x32x16_bf16(b0, qr[d0], p0, 0, 0, 0);
;         p1 = __builtin_amdgcn_mfma_f32_32x32x16_bf16(b1, qr[d0], p1, 0, 0, 0); }
; }
; __device__ __forceinline__ void attn_block(const BlockRef& cur, const BlockRef& nxt, char* lds, Seam& S) {
;     ...
;     const bool even = (NT & 1) == 0;
;     const bool actL = KBASE(NT - 1) <= (qlo | 63), actP = KBASE(NT - 2) <= (qlo | 63);
;     if (even) { SBAR(); if (actL) qkt<1>(pB0, pB1, K_lds, r32, hi, S.qr); else { const float NEG_ = -__builtin_inff(); _Pragma("unroll") for (int r_ = 0; r_ < 16; ++r_) { pB0[r_] = NEG_; pB1[r_] = NEG_; } } SBAR(); }
;     { const int sr_ = sr; (void)sr_; SLOAD_H(nxt.K, nxt.V, 0); SBAR();
; #pragma unroll
;       for (int d0 = 0; d0 < 8; ++d0) S.qr[d0] = load8(nxt.Q + (size_t)(wid * QBLK + r32) * D + d0 * 16 + hi * 8); }
;     SBAR();
;     finishSM(pA0, pA1, alA, l_reg, pa0, pa1, pa2, pa3); SBAR();
;     if (actP) pv_tile<0>(o, vb0, pa0, pa1, pa2, pa3);
;     if (even) { MASKT(pB0, pB1, NT - 1); partialSM(pB0, pB1, m_reg, mnB, alB); __syncthreads(); RESC(alB);
;         finishSM(pB0, pB1, alB, l_reg, pa0, pa1, pa2, pa3); SBAR(); if (actL) pv_tile<1>(o, vb0, pa0, pa1, pa2, pa3); }
.LBB0_334:
	v_add_u32_e32 v104, 0x80, v212
	v_ashrrev_i32_e32 v105, 31, v104
	v_add_u32_e32 v106, 0xa0, v212
	v_ashrrev_i32_e32 v107, 31, v106
	v_lshlrev_b64 v[104:105], 8, v[104:105]
	v_lshlrev_b64 v[106:107], 8, v[106:107]
	v_lshl_add_u64 v[104:105], v[208:209], 0, v[104:105]
	v_lshl_add_u64 v[106:107], v[208:209], 0, v[106:107]
	global_load_dwordx4 v[108:111], v[106:107], off
	global_load_dwordx4 v[104:107], v[104:105], off
	s_bitcmp0_b32 s29, 6
	s_cselect_b64 s[50:51], -1, 0
	s_and_b32 s54, s78, 0xffffffc0
	s_sub_i32 s40, s54, 64
	s_cmp_gt_i32 s40, s49
	s_cselect_b64 s[42:43], -1, 0
	s_cmp_le_i32 s40, s49
	s_cselect_b64 s[40:41], -1, 0
	s_mov_b64 s[52:53], -1
	s_and_b64 vcc, exec, s[50:51]
	s_cbranch_vccnz .LBB0_336
	s_mov_b64 s[52:53], 0
.LBB0_336:
	v_cndmask_b32_e64 v96, 0, 1, s[40:41]
	s_andn2_b64 vcc, exec, s[52:53]
	v_cmp_ne_u32_e64 s[40:41], 1, v96
	s_cbranch_vccnz .LBB0_341
	s_and_b64 vcc, exec, s[40:41]
	s_cbranch_vccnz .LBB0_339
	v_xor_b32_e32 v250, 0x80, v201
	v_xor_b32_e32 v251, 0x80, v230
	v_xor_b32_e32 v252, 0x80, v229
	v_xor_b32_e32 v253, 0x80, v207
	ds_read_b128 v[64:67], v201 offset:49152
	ds_read_b128 v[80:83], v201 offset:57344
	ds_read_b128 v[96:99], v230 offset:49152
	ds_read_b128 v[100:103], v230 offset:57344
	s_waitcnt lgkmcnt(3)
	v_mfma_f32_32x32x16_bf16 v[64:79], v[64:67], v[156:159], 0
	s_waitcnt lgkmcnt(2)
	v_mfma_f32_32x32x16_bf16 v[80:95], v[80:83], v[156:159], 0
	s_waitcnt lgkmcnt(1)
	v_mfma_f32_32x32x16_bf16 v[64:79], v[96:99], v[152:155], v[64:79]
	s_waitcnt lgkmcnt(0)
	v_mfma_f32_32x32x16_bf16 v[80:95], v[100:103], v[152:155], v[80:95]
	ds_read_b128 v[96:99], v229 offset:49152
	ds_read_b128 v[100:103], v229 offset:57344
	s_waitcnt lgkmcnt(1)
	v_mfma_f32_32x32x16_bf16 v[64:79], v[96:99], v[148:151], v[64:79]
	s_waitcnt lgkmcnt(0)
	v_mfma_f32_32x32x16_bf16 v[80:95], v[100:103], v[148:151], v[80:95]
	ds_read_b128 v[96:99], v207 offset:49152
	ds_read_b128 v[100:103], v207 offset:57344
	s_waitcnt lgkmcnt(1)
	v_mfma_f32_32x32x16_bf16 v[64:79], v[96:99], v[144:147], v[64:79]
	s_waitcnt lgkmcnt(0)
	v_mfma_f32_32x32x16_bf16 v[80:95], v[100:103], v[144:147], v[80:95]
	ds_read_b128 v[96:99], v250 offset:49152
	ds_read_b128 v[100:103], v250 offset:57344
	s_waitcnt lgkmcnt(1)
	v_mfma_f32_32x32x16_bf16 v[64:79], v[96:99], v[140:143], v[64:79]
	s_waitcnt lgkmcnt(0)
	v_mfma_f32_32x32x16_bf16 v[80:95], v[100:103], v[140:143], v[80:95]
	ds_read_b128 v[96:99], v251 offset:49152
	ds_read_b128 v[100:103], v251 offset:57344
	s_waitcnt lgkmcnt(1)
	v_mfma_f32_32x32x16_bf16 v[64:79], v[96:99], v[136:139], v[64:79]
	s_waitcnt lgkmcnt(0)
	v_mfma_f32_32x32x16_bf16 v[80:95], v[100:103], v[136:139], v[80:95]
	ds_read_b128 v[96:99], v252 offset:49152
	ds_read_b128 v[100:103], v252 offset:57344
	s_waitcnt lgkmcnt(1)
	v_mfma_f32_32x32x16_bf16 v[64:79], v[96:99], v[132:135], v[64:79]
	s_waitcnt lgkmcnt(0)
	v_mfma_f32_32x32x16_bf16 v[80:95], v[100:103], v[132:135], v[80:95]
	ds_read_b128 v[96:99], v253 offset:49152
	ds_read_b128 v[100:103], v253 offset:57344
	s_waitcnt lgkmcnt(1)
	v_mfma_f32_32x32x16_bf16 v[64:79], v[96:99], v[128:131], v[64:79]
	s_waitcnt lgkmcnt(0)
	v_mfma_f32_32x32x16_bf16 v[80:95], v[100:103], v[128:131], v[80:95]
	s_branch .LBB0_340

; #define SBAR() __builtin_amdgcn_sched_barrier(0)
; #define SLOAD_H(Kp, Vp, k0) do { S.st_v0 = load8(ROW(Vp, k0, sr)); S.st_v1 = load8(ROW(Vp, k0, 32 + sr)); S.st_k0 = load8(ROW(Kp, k0, sr)); S.st_k1 = load8(ROW(Kp, k0, 32 + sr)); } while (0)
; #define RESC(a) do { if (__any((a) < 1.f)) { if (hi == 0) al_l[r32] = (a); asm volatile("s_waitcnt lgkmcnt(0)" ::: "memory");              \
;                      for (int d_ = 0; d_ < 4; ++d_) for (int r = 0; r < 16; ++r) o[d_][r] *= al_l[crow(r, hi)]; } } while (0)
; #define MASKT(P0_, P1_, t) do { if (KBASE(t) > (qlo | 63)) { const float NEG_ = -__builtin_inff(); _Pragma("unroll") for (int r_ = 0; r_ < 16; ++r_) { P0_[r_] = NEG_; P1_[r_] = NEG_; } } } while (0)
; __device__ __forceinline__ void attn_block(const BlockRef& cur, const BlockRef& nxt, char* lds, Seam& S) {
;     ...
;     if (even) { SBAR(); if (actL) qkt<1>(pB0, pB1, K_lds, r32, hi, S.qr); else { const float NEG_ = -__builtin_inff(); _Pragma("unroll") for (int r_ = 0; r_ < 16; ++r_) { pB0[r_] = NEG_; pB1[r_] = NEG_; } } SBAR(); }
;     { const int sr_ = sr; (void)sr_; SLOAD_H(nxt.K, nxt.V, 0); SBAR();
; #pragma unroll
;       for (int d0 = 0; d0 < 8; ++d0) S.qr[d0] = load8(nxt.Q + (size_t)(wid * QBLK + r32) * D + d0 * 16 + hi * 8); }
;     SBAR();
;     finishSM(pA0, pA1, alA, l_reg, pa0, pa1, pa2, pa3); SBAR();
;     if (actP) pv_tile<0>(o, vb0, pa0, pa1, pa2, pa3);
;     if (even) { MASKT(pB0, pB1, NT - 1); partialSM(pB0, pB1, m_reg, mnB, alB); __syncthreads(); RESC(alB);
;         finishSM(pB0, pB1, alB, l_reg, pa0, pa1, pa2, pa3); SBAR(); if (actL) pv_tile<1>(o, vb0, pa0, pa1, pa2, pa3); }
.LBB0_340:
	s_waitcnt vmcnt(0)
	ds_write_b128 v231, v[104:107] offset:16384
	ds_write_b128 v232, v[108:111] offset:16384
	s_waitcnt lgkmcnt(0)

; #define PG8_STAGE(bufoff, gbase, voff) do { _Pragma("unroll") for (int _i = 0; _i < 2; ++_i) \
;         __builtin_amdgcn_global_load_lds((const unsigned*)((const char*)(gbase) + (voff)[_i]), (PG8_LAS unsigned*)(lds + (bufoff) + ldsw + _i * 8192), 16, 0, 0); } while (0)
; #define PG8_BAR __builtin_amdgcn_s_barrier()
; template <class Epi, class Sched, bool ALIGN_EPI = false, bool SP2 = false>
; __device__ __forceinline__ void gemm_phase(PG8_LAS unsigned char* lds, const Gemm g, const Sched& S, const Epi& E) {
;     ...
;     const int tid = tid_, wid = __builtin_amdgcn_readfirstlane(tid >> 6), lane = tid & 63, wr = wid >> 2, wc = wid & 3, fr = lane & 15, fq = lane >> 4;
;     const int K = g.K, nt = K / BK;
;     unsigned voffA[2], voffB[2];
; #pragma unroll
;     for (int i = 0; i < 2; ++i) { int R, C; stage_rc(tid * 16 + i * 8192, R, C); const int Rb = Epi::PERM ? ((R & ~31) + perm32(R & 31)) : R;
;         voffA[i] = (unsigned)(R * K + C) * 2u; voffB[i] = (unsigned)(Rb * K + C) * 2u; }
;     const size_t kstep = (size_t)(BK * 2);
;     const size_t hstep = (size_t)HALF * K * 2;
;     const size_t tstep = 2 * hstep;
;     const unsigned ldsw = (unsigned)wid * 1024u;
;     const int aoff = lds_byte(wr * 64 + fr, fq * 8), boff = lds_byte(wc * 32 + fr, fq * 8);
;     ...
;     Unit cur, nxt; int ui = 0;
;     if (!S.next(0, cur)) return;
;     f32x4 acc[2][2][4][2];
; #pragma unroll
;     for (int a = 0; a < 2; ++a)
; #pragma unroll
;         for (int b = 0; b < 2; ++b)
; #pragma unroll
;             for (int m = 0; m < 4; ++m)
; #pragma unroll
;                 for (int n = 0; n < 2; ++n) acc[a][b][m][n] = (f32x4){0.f, 0.f, 0.f, 0.f};
;     bf16x8 At[4][2], B0[2][2], B1[2][2];
;     const char* cA = (const char*)g.A + (size_t)cur.pm * tstep; const char* cB = (const char*)g.Bt + (size_t)cur.pn * tstep;
;     S.a_ready(cur);
;     if constexpr (SP2) {
;         PG8_STAGE(PG8_SB(0, 0), cB, voffB); PG8_STAGE(PG8_SB(0, 1), cB + hstep, voffB); PG8_STAGE(PG8_SA(0, 0), cA, voffA); PG8_STAGE(PG8_SA(0, 1), cA + hstep, voffA);
;         if (wr == 1) PG8_BAR;
;         PG8_WAIT_V(2); PG8_BAR;
; __global__ void __launch_bounds__(NTHR, 2) mega_fwd(Args args) {
;     ...
;         pg8::StaticOrder S; S.init(T, DM, G, bx);
;         { pg8::Gemm g{YC, WC, T, DM, CW}; pg8::EpiMerge<false> E{MG, GT}; pg8::gemm_phase<pg8::EpiMerge<false>, pg8::StaticOrder, true, true>(L, g, S, E); }
.LBB0_540:
	s_or_b64 exec, exec, s[14:15]
	s_nop 0
	s_nop 0
	s_nop 0
	s_nop 0
	s_cmpk_lt_i32 s2, 0x400
	s_mov_b64 s[22:23], s[0:1]
	s_mov_b64 s[16:17], s[0:1]
	s_mov_b64 s[24:25], s[0:1]
	s_mov_b64 s[18:19], s[0:1]
	s_mov_b64 s[14:15], s[0:1]
	s_waitcnt lgkmcnt(0)
	s_barrier
	s_cselect_b64 s[48:49], -1, 0
	s_lshr_b32 s13, s33, 29
	s_add_i32 s13, s2, s13
	s_load_dwordx2 s[14:15], s[14:15], 0xc8
	s_ashr_i32 s56, s13, 3
	s_and_b32 s13, s13, -8
	s_load_dwordx2 s[20:21], s[16:17], 0xc8
	s_nop 0
	s_load_dwordx2 s[18:19], s[18:19], 0xc8
	s_mov_b64 s[16:17], s[0:1]
	s_sub_i32 s59, s2, s13
	s_cmp_lt_i32 s59, 0
	s_load_dwordx2 s[16:17], s[16:17], 0xc8
	s_cselect_b64 s[42:43], -1, 0
	s_lshl_b32 s57, s59, 7
	s_waitcnt lgkmcnt(0)
	s_add_u32 s14, s14, 0x2f800000
	s_addc_u32 s15, s15, 0
	s_waitcnt vmcnt(27)
	v_mov_b32_e32 v14, v216
	s_cmpk_gt_i32 s2, 0x3ff
	s_mul_i32 s58, s59, 0x81
	s_nop 0
	v_readfirstlane_b32 s28, v14
	s_cbranch_scc1 .LBB0_560
	v_lshlrev_b32_e32 v0, 4, v14
	v_add_u32_e32 v1, 0x2000, v0
	v_ashrrev_i32_e32 v2, 31, v1
	v_lshrrev_b32_e32 v2, 22, v2
	v_add_u32_e32 v2, v1, v2
	v_ashrrev_i32_e32 v8, 10, v2
	v_mul_i32_i24_e32 v2, 0x400, v8
	v_sub_u32_e32 v1, v1, v2
	v_lshrrev_b32_e32 v2, 4, v1
	v_bitop3_b32 v1, v2, v1, 32 bitop3:0x6c
	v_ashrrev_i32_e32 v2, 31, v1
	s_load_dwordx2 s[22:23], s[22:23], 0xc8
	s_nop 0
	s_load_dwordx2 s[24:25], s[24:25], 0xc8
	v_lshrrev_b32_e32 v2, 26, v2
	v_add_u32_e32 v2, v1, v2
	v_lshlrev_b32_e32 v3, 3, v8
	v_ashrrev_i32_e32 v9, 6, v2
	v_and_b32_e32 v3, -16, v3
	v_add_u32_e32 v3, v9, v3
	s_waitcnt lgkmcnt(0)
	s_add_u32 s13, s22, 0x3b800000
	v_and_b32_e32 v4, 3, v9
	s_mov_b32 s22, 0x1fffe0
	v_lshrrev_b32_e32 v5, 2, v3
	v_lshlrev_b32_e32 v6, 1, v3
	v_and_b32_e32 v2, 0xc0, v2
	v_and_or_b32 v4, v3, s22, v4
	v_and_b32_e32 v5, 4, v5
	v_and_b32_e32 v6, 24, v6
	v_sub_u32_e32 v1, v1, v2
	v_mov_b32_e32 v2, 1
	v_or3_b32 v4, v4, v5, v6
	v_lshlrev_b32_e32 v5, 5, v8
	v_ashrrev_i16_sdwa v1, v2, sext(v1) dst_sel:DWORD dst_unused:UNUSED_PAD src0_sel:DWORD src1_sel:BYTE_0
	v_and_b32_e32 v5, 32, v5
	v_bfe_i32 v10, v1, 0, 16
	v_add_lshl_u32 v1, v5, v10, 1
	s_waitcnt vmcnt(6)
	v_lshl_add_u32 v152, v4, 11, v1
	v_lshl_add_u32 v154, v3, 11, v1
	v_bfe_i32 v1, v14, 27, 1
	v_lshrrev_b32_e32 v1, 22, v1
	v_add_u32_e32 v1, v0, v1
	v_and_b32_e32 v1, 0xfffffc00, v1
	v_sub_u32_e32 v0, v0, v1
	v_lshrrev_b32_e32 v1, 4, v0
	v_ashrrev_i32_e32 v3, 31, v14
	v_bitop3_b32 v0, v1, v0, 32 bitop3:0x6c
	v_lshrrev_b32_e32 v3, 26, v3
	v_ashrrev_i32_e32 v1, 31, v0
	v_add_u32_e32 v3, v14, v3
	s_addc_u32 s47, s23, 0
	v_lshrrev_b32_e32 v1, 26, v1
	v_ashrrev_i32_e32 v12, 6, v3
	s_add_u32 s60, s24, 0x2600000
	v_add_u32_e32 v1, v0, v1
	v_lshlrev_b32_e32 v3, 3, v12
	s_addc_u32 s61, s25, 0
	s_ashr_i32 s26, s28, 6
	v_ashrrev_i32_e32 v11, 6, v1
	v_and_b32_e32 v3, -16, v3
	s_ashr_i32 s27, s28, 8
	s_lshl_b32 s62, s26, 10
	v_add_u32_e32 v3, v11, v3
	v_and_b32_e32 v4, 3, v11
	v_and_or_b32 v4, v3, s22, v4
	s_and_b64 s[22:23], s[42:43], exec
	s_cselect_b32 s22, s58, s57
	s_add_i32 s22, s22, s56
	s_ashr_i32 s23, s22, 31
	s_lshr_b32 s23, s23, 27
	s_add_i32 s23, s22, s23
	s_ashr_i32 s24, s23, 5
	s_and_b32 s23, s23, 0xffe0
	s_sub_i32 s22, s22, s23
	s_bfe_i32 s23, s22, 0x80000
	s_bfe_u32 s23, s23, 0x2000d
	s_add_i32 s23, s22, s23
	s_lshl_b32 s25, s24, 2
	s_bfe_i32 s24, s23, 0x80000
	s_and_b32 s23, s23, 0xfc
	s_sub_i32 s22, s22, s23
	s_sext_i32_i16 s24, s24
	s_sext_i32_i8 s22, s22
	v_lshrrev_b32_e32 v5, 2, v3
	v_lshlrev_b32_e32 v6, 1, v3
	v_and_b32_e32 v1, 0xc0, v1
	s_lshr_b32 s24, s24, 2
	s_add_i32 s44, s25, s22
	v_and_b32_e32 v5, 4, v5
	v_and_b32_e32 v6, 24, v6
	v_sub_u32_e32 v0, v0, v1
	s_ashr_i32 s45, s44, 31
	s_bfe_i64 s[30:31], s[24:25], 0x100000
	v_or3_b32 v4, v4, v5, v6
	v_lshlrev_b32_e32 v5, 5, v12
	v_ashrrev_i16_sdwa v0, v2, sext(v0) dst_sel:DWORD dst_unused:UNUSED_PAD src0_sel:DWORD src1_sel:BYTE_0
	s_lshl_b64 s[22:23], s[44:45], 19
	s_lshl_b64 s[30:31], s[30:31], 19
	v_and_b32_e32 v5, 32, v5
	v_bfe_i32 v13, v0, 0, 16
	s_add_u32 s52, s60, s30
	v_add_lshl_u32 v0, v5, v13, 1
	s_addc_u32 s53, s61, s31
	s_add_i32 s63, s62, 0
	v_lshl_add_u32 v156, v4, 11, v0
	s_add_i32 m0, s63, 0x10000
	v_lshl_add_u32 v158, v3, 11, v0
	global_load_lds_dwordx4 v156, s[52:53]
	s_add_i32 m0, s63, 0x12000
	s_add_u32 s30, s52, 0x40000
	global_load_lds_dwordx4 v152, s[52:53]
	s_addc_u32 s31, s53, 0
	s_add_i32 m0, s63, 0x14000
	v_mov_b32_e32 v157, 0
	global_load_lds_dwordx4 v156, s[30:31]
	s_add_i32 m0, s63, 0x16000
	s_add_u32 s50, s13, s22
	s_addc_u32 s51, s47, s23
	s_add_i32 s64, s63, 0x2000
	global_load_lds_dwordx4 v152, s[30:31]
	s_mov_b32 m0, s63
	s_add_u32 s22, s50, 0x40000
	global_load_lds_dwordx4 v158, s[50:51]
	s_mov_b32 m0, s64
	s_addc_u32 s23, s51, 0
	s_add_i32 s65, s63, 0x4000
	global_load_lds_dwordx4 v154, s[50:51]
	s_mov_b32 m0, s65
	s_add_i32 s66, s63, 0x6000
	global_load_lds_dwordx4 v158, s[22:23]
	s_mov_b32 m0, s66
	v_mov_b32_e32 v153, v157
	global_load_lds_dwordx4 v154, s[22:23]
	v_mov_b32_e32 v159, v157
	v_mov_b32_e32 v155, v157
	s_cmp_eq_u32 s27, 1
	v_lshl_add_u64 v[6:7], s[52:53], 0, v[156:157]
	v_lshl_add_u64 v[4:5], s[52:53], 0, v[152:153]
	v_lshl_add_u64 v[0:1], s[50:51], 0, v[158:159]
	s_cselect_b64 s[22:23], -1, 0
	s_cmp_lg_u32 s27, 1
	v_lshl_add_u64 v[2:3], s[50:51], 0, v[154:155]
	s_cbranch_scc1 .LBB0_543
	s_barrier

; __global__ void __launch_bounds__(NTHR, 2) mega_fwd(Args args) {
	.amdhsa_kernel _Z8mega_fwd4Args
		.amdhsa_group_segment_fixed_size 0
		.amdhsa_private_segment_fixed_size 0
		.amdhsa_kernarg_size 464
		.amdhsa_user_sgpr_count 2
		.amdhsa_user_sgpr_dispatch_ptr 0
		.amdhsa_user_sgpr_queue_ptr 0
		.amdhsa_user_sgpr_kernarg_segment_ptr 1
		.amdhsa_user_sgpr_dispatch_id 0
		.amdhsa_user_sgpr_kernarg_preload_length 0
		.amdhsa_user_sgpr_kernarg_preload_offset 0
		.amdhsa_user_sgpr_private_segment_size 0
		.amdhsa_uses_dynamic_stack 0
		.amdhsa_enable_private_segment 0
		.amdhsa_system_sgpr_workgroup_id_x 1
		.amdhsa_system_sgpr_workgroup_id_y 0
		.amdhsa_system_sgpr_workgroup_id_z 0
		.amdhsa_system_sgpr_workgroup_info 0
		.amdhsa_system_vgpr_workitem_id 2
		.amdhsa_next_free_vgpr 256
		.amdhsa_next_free_sgpr 98
		.amdhsa_accum_offset 256
		.amdhsa_reserve_vcc 1
		.amdhsa_float_round_mode_32 0
		.amdhsa_float_round_mode_16_64 0
		.amdhsa_float_denorm_mode_32 3
		.amdhsa_float_denorm_mode_16_64 3
		.amdhsa_dx10_clamp 1
		.amdhsa_ieee_mode 1
		.amdhsa_fp16_overflow 0
		.amdhsa_tg_split 0
		.amdhsa_exception_fp_ieee_invalid_op 0
		.amdhsa_exception_fp_denorm_src 0
		.amdhsa_exception_fp_ieee_div_zero 0
		.amdhsa_exception_fp_ieee_overflow 0
		.amdhsa_exception_fp_ieee_underflow 0
		.amdhsa_exception_fp_ieee_inexact 0
		.amdhsa_exception_int_div_zero 0
	.end_amdhsa_kernel

; __global__ void __launch_bounds__(NTHR, 2) mega_fwd(Args args) {
amdhsa.kernels:
  - .agpr_count:     0
    .args:
      - .offset:         0
        .size:           208
        .value_kind:     by_value
      - .offset:         208
        .size:           4
        .value_kind:     hidden_block_count_x
      - .offset:         212
        .size:           4
        .value_kind:     hidden_block_count_y
      - .offset:         216
        .size:           4
        .value_kind:     hidden_block_count_z
      - .offset:         220
        .size:           2
        .value_kind:     hidden_group_size_x
      - .offset:         222
        .size:           2
        .value_kind:     hidden_group_size_y
      - .offset:         224
        .size:           2
        .value_kind:     hidden_group_size_z
      - .offset:         226
        .size:           2
        .value_kind:     hidden_remainder_x
      - .offset:         228
        .size:           2
        .value_kind:     hidden_remainder_y
      - .offset:         230
        .size:           2
        .value_kind:     hidden_remainder_z
      - .offset:         248
        .size:           8
        .value_kind:     hidden_global_offset_x
      - .offset:         256
        .size:           8
        .value_kind:     hidden_global_offset_y
      - .offset:         264
        .size:           8
        .value_kind:     hidden_global_offset_z
      - .offset:         272
        .size:           2
        .value_kind:     hidden_grid_dims
      - .offset:         296
        .size:           8
        .value_kind:     hidden_multigrid_sync_arg
      - .offset:         328
        .size:           4
        .value_kind:     hidden_dynamic_lds_size
    .group_segment_fixed_size: 0
    .kernarg_segment_align: 8
    .kernarg_segment_size: 464
    .language:       OpenCL C
    .language_version:
      - 2
      - 0
    .max_flat_workgroup_size: 512
    .name:           _Z8mega_fwd4Args
    .private_segment_fixed_size: 0
    .sgpr_count:     104
    .sgpr_spill_count: 60
    .symbol:         _Z8mega_fwd4Args.kd
    .uniform_work_group_size: 1
    .uses_dynamic_stack: false
    .vgpr_count:     256
    .vgpr_spill_count: 0
    .wavefront_size: 64
